# residual phases: the xor-1/2/4/8 hops of the wave reductions done with DPP row ops instead of ds_bpermute round trips (same pairing, bit-identical sums)
# baseline (speedup 1.0000x reference)
; __device__ __forceinline__ float shx(float v, int m, int lane) { return __builtin_bit_cast(float, __builtin_amdgcn_ds_bpermute((lane ^ m) << 2, __builtin_bit_cast(int, v))); }
; template <int RB> __device__ __forceinline__ void res_phase(float* xout, const bf16_t* mix, const float* ssp, const float* gain, bf16_t* XN, float* rinv, int gw, int ngw, int lane) {
;     ...
;     for (int row0 = rbase; row0 < rend; row0 += rstep) {
;         float ps[RB]; u32x2 xw[RB][4], mw[RB][4];
; #pragma unroll
;         for (int i = 0; i < RB; ++i) { const int row = row0 + i; ps[i] = ssp[(size_t)row * 16 + (lane & 15)];
;             const u32x2* xr = (const u32x2*)(XN + (size_t)row * DM) + lane; const u32x2* mr = (const u32x2*)(mix + (size_t)row * DM) + lane;
; #pragma unroll
;             for (int j = 0; j < 4; ++j) { xw[i][j] = xr[64 * j]; mw[i][j] = mr[64 * j]; } }
; #pragma unroll
;         for (int i = 0; i < RB; ++i) { const int row = row0 + i; float p = ps[i];
;             p += shx(p, 1, lane); p += shx(p, 2, lane); p += shx(p, 4, lane); p += shx(p, 8, lane);
;             const float rm = 1.0f / sqrtf(p * (1.0f / DM) + EPS);
;             f32x4 v[4]; float s = 0.f;
; #pragma unroll
;             for (int j = 0; j < 4; ++j) { const u32x2 a = xw[i][j], m = mw[i][j];
;                 f32x4 xv; xv[0] = __builtin_bit_cast(float, a.x << 16); xv[1] = __builtin_bit_cast(float, a.x & 0xffff0000u); xv[2] = __builtin_bit_cast(float, a.y << 16); xv[3] = __builtin_bit_cast(float, a.y & 0xffff0000u);
;                 f32x4 mv; mv[0] = __builtin_bit_cast(float, m.x << 16); mv[1] = __builtin_bit_cast(float, m.x & 0xffff0000u); mv[2] = __builtin_bit_cast(float, m.y << 16); mv[3] = __builtin_bit_cast(float, m.y & 0xffff0000u);
;                 v[j] = xv + mv * rm * gv[j]; s += (v[j][0] * v[j][0] + v[j][1] * v[j][1]) + (v[j][2] * v[j][2] + v[j][3] * v[j][3]); }
.LBB0_467:
	v_lshl_add_u64 v[26:27], s[0:1], 0, v[24:25]
	v_add_co_u32_e32 v26, vcc, 0x400000, v26
	v_lshl_add_u64 v[62:63], s[0:1], 0, v[22:23]
	s_nop 0
	v_addc_co_u32_e32 v27, vcc, 0, v27, vcc
	flat_load_dword v98, v[26:27]
	v_add_co_u32_e32 v80, vcc, 0x3800000, v62
	s_add_i32 s80, s2, 2
	s_nop 0
	v_addc_co_u32_e32 v81, vcc, 0, v63, vcc
	flat_load_dwordx2 v[94:95], v[80:81]
	v_add_co_u32_e32 v28, vcc, 0x7800000, v62
	s_ashr_i32 s81, s80, 31
	s_waitcnt lgkmcnt(0)
	v_addc_co_u32_e32 v29, vcc, 0, v63, vcc
	flat_load_dwordx2 v[96:97], v[28:29]
	flat_load_dwordx2 v[92:93], v[80:81] offset:512
	flat_load_dwordx2 v[90:91], v[28:29] offset:512
	flat_load_dwordx2 v[88:89], v[80:81] offset:1024
	flat_load_dwordx2 v[86:87], v[28:29] offset:1024
	flat_load_dwordx2 v[84:85], v[80:81] offset:1536
	flat_load_dwordx2 v[82:83], v[28:29] offset:1536
	flat_load_dword v107, v[26:27] offset:64
	flat_load_dwordx2 v[78:79], v[80:81] offset:2048
	flat_load_dwordx2 v[76:77], v[28:29] offset:2048
	flat_load_dwordx2 v[74:75], v[80:81] offset:2560
	flat_load_dwordx2 v[72:73], v[28:29] offset:2560
	flat_load_dwordx2 v[70:71], v[80:81] offset:3072
	flat_load_dwordx2 v[68:69], v[28:29] offset:3072
	flat_load_dwordx2 v[66:67], v[80:81] offset:3584
	flat_load_dwordx2 v[64:65], v[28:29] offset:3584
	s_lshl_b64 s[10:11], s[80:81], 6
	s_add_i32 s78, s2, 3
	v_lshl_add_u64 v[26:27], v[16:17], 0, s[10:11]
	s_lshl_b64 s[10:11], s[80:81], 11
	s_ashr_i32 s79, s78, 31
	flat_load_dword v106, v[26:27]
	v_lshl_add_u64 v[44:45], v[18:19], 0, s[10:11]
	v_lshl_add_u64 v[26:27], v[20:21], 0, s[10:11]
	s_lshl_b64 s[10:11], s[78:79], 6
	flat_load_dwordx2 v[60:61], v[44:45]
	flat_load_dwordx2 v[58:59], v[26:27]
	flat_load_dwordx2 v[56:57], v[44:45] offset:512
	flat_load_dwordx2 v[54:55], v[26:27] offset:512
	flat_load_dwordx2 v[52:53], v[44:45] offset:1024
	flat_load_dwordx2 v[50:51], v[26:27] offset:1024
	flat_load_dwordx2 v[48:49], v[44:45] offset:1536
	flat_load_dwordx2 v[46:47], v[26:27] offset:1536
	v_lshl_add_u64 v[26:27], v[16:17], 0, s[10:11]
	s_lshl_b64 s[10:11], s[78:79], 11
	flat_load_dword v105, v[26:27]
	v_lshl_add_u64 v[26:27], v[18:19], 0, s[10:11]
	v_lshl_add_u64 v[28:29], v[20:21], 0, s[10:11]
	flat_load_dwordx2 v[42:43], v[26:27]
	flat_load_dwordx2 v[40:41], v[28:29]
	flat_load_dwordx2 v[38:39], v[26:27] offset:512
	flat_load_dwordx2 v[36:37], v[28:29] offset:512
	flat_load_dwordx2 v[34:35], v[26:27] offset:1024
	flat_load_dwordx2 v[32:33], v[28:29] offset:1024
	flat_load_dwordx2 v[30:31], v[26:27] offset:1536
	s_nop 0
	flat_load_dwordx2 v[28:29], v[28:29] offset:1536
	s_waitcnt vmcnt(0) lgkmcnt(0)
	s_nop 0
	s_waitcnt lgkmcnt(0)
	s_nop 1
	v_add_f32_dpp v98, v98, v98 quad_perm:[1,0,3,2] row_mask:0xf bank_mask:0xf
	s_nop 0
	s_waitcnt lgkmcnt(0)
	s_nop 1
	v_add_f32_dpp v98, v98, v98 quad_perm:[2,3,0,1] row_mask:0xf bank_mask:0xf
	s_nop 0
	s_waitcnt lgkmcnt(0)
	s_nop 1
	v_add_f32_dpp v98, v98, v98 row_half_mirror row_mask:0xf bank_mask:0xf
	s_nop 0
	s_waitcnt lgkmcnt(0)
	s_nop 1
	v_add_f32_dpp v98, v98, v98 row_mirror row_mask:0xf bank_mask:0xf
	v_fmamk_f32 v98, v98, 0x3a800000, v217
	v_cmp_gt_f32_e32 vcc, s59, v98
	v_mul_f32_e32 v108, 0x4f800000, v98
	s_nop 0
	v_cndmask_b32_e32 v98, v98, v108, vcc
	v_sqrt_f32_e32 v108, v98
	s_nop 0
	v_add_u32_e32 v109, -1, v108
	v_fma_f32 v110, -v109, v108, v98
	v_cmp_ge_f32_e64 s[40:41], 0, v110
	v_add_u32_e32 v110, 1, v108
	s_nop 0
	v_cndmask_b32_e64 v109, v108, v109, s[40:41]
	v_fma_f32 v108, -v110, v108, v98
	v_cmp_lt_f32_e64 s[40:41], 0, v108
	s_nop 1
	v_cndmask_b32_e64 v108, v109, v110, s[40:41]
	v_mul_f32_e32 v109, 0x37800000, v108
	v_cndmask_b32_e32 v108, v108, v109, vcc
	v_cmp_class_f32_e32 vcc, v98, v218
	s_nop 1
	v_cndmask_b32_e32 v98, v108, v98, vcc
	v_div_scale_f32 v108, s[10:11], v98, v98, 1.0
	v_rcp_f32_e32 v109, v108
	s_nop 0
	v_fma_f32 v110, -v108, v109, 1.0
	v_fmac_f32_e32 v109, v110, v109
	v_div_scale_f32 v110, vcc, 1.0, v98, 1.0
	v_mul_f32_e32 v111, v110, v109
	v_fma_f32 v112, -v108, v111, v110
	v_fmac_f32_e32 v111, v112, v109
	v_fma_f32 v108, -v108, v111, v110
	v_div_fmas_f32 v108, v108, v109, v111
	v_div_fixup_f32 v98, v108, v98, 1.0
	v_lshlrev_b32_e32 v110, 16, v96
	v_and_b32_e32 v111, 0xffff0000, v96
	v_lshlrev_b32_e32 v96, 16, v97
	v_and_b32_e32 v97, 0xffff0000, v97
	v_lshlrev_b32_e32 v108, 16, v94
	v_and_b32_e32 v109, 0xffff0000, v94
	v_pk_mul_f32 v[112:113], v[98:99], v[96:97] op_sel_hi:[0,1]
	v_pk_mul_f32 v[96:97], v[98:99], v[110:111] op_sel_hi:[0,1]
	v_pk_fma_f32 v[96:97], v[0:1], v[96:97], v[108:109]
	v_lshlrev_b32_e32 v108, 16, v92
	v_and_b32_e32 v109, 0xffff0000, v92
	v_lshlrev_b32_e32 v110, 16, v93
	v_and_b32_e32 v111, 0xffff0000, v93
	v_lshlrev_b32_e32 v92, 16, v90
	v_and_b32_e32 v93, 0xffff0000, v90
	v_lshlrev_b32_e32 v90, 16, v91
	v_and_b32_e32 v91, 0xffff0000, v91
	v_pk_mul_f32 v[90:91], v[98:99], v[90:91] op_sel_hi:[0,1]
	v_pk_mul_f32 v[92:93], v[98:99], v[92:93] op_sel_hi:[0,1]
	v_pk_fma_f32 v[90:91], v[6:7], v[90:91], v[110:111]
	v_lshlrev_b32_e32 v110, 16, v86
	v_and_b32_e32 v111, 0xffff0000, v86
	v_pk_fma_f32 v[92:93], v[4:5], v[92:93], v[108:109]
	v_lshlrev_b32_e32 v108, 16, v88
	v_and_b32_e32 v109, 0xffff0000, v88
	v_lshlrev_b32_e32 v86, 16, v87
	v_and_b32_e32 v87, 0xffff0000, v87
	v_pk_mul_f32 v[110:111], v[98:99], v[110:111] op_sel_hi:[0,1]
	v_lshlrev_b32_e32 v94, 16, v95
	v_and_b32_e32 v95, 0xffff0000, v95
	v_lshlrev_b32_e32 v88, 16, v89
	v_and_b32_e32 v89, 0xffff0000, v89
	v_pk_mul_f32 v[86:87], v[98:99], v[86:87] op_sel_hi:[0,1]
	v_pk_fma_f32 v[108:109], v[8:9], v[110:111], v[108:109]
	v_lshlrev_b32_e32 v110, 16, v82
	v_and_b32_e32 v111, 0xffff0000, v82
	v_lshlrev_b32_e32 v82, 16, v83
	v_and_b32_e32 v83, 0xffff0000, v83
	v_pk_fma_f32 v[94:95], v[2:3], v[112:113], v[94:95]
	v_pk_fma_f32 v[86:87], v[10:11], v[86:87], v[88:89]
	v_lshlrev_b32_e32 v88, 16, v84
	v_and_b32_e32 v89, 0xffff0000, v84
	v_lshlrev_b32_e32 v84, 16, v85
	v_and_b32_e32 v85, 0xffff0000, v85
	v_pk_mul_f32 v[82:83], v[98:99], v[82:83] op_sel_hi:[0,1]
	v_pk_fma_f32 v[84:85], v[14:15], v[82:83], v[84:85]
	v_mul_f32_e32 v82, v97, v97
	v_mul_f32_e32 v83, v95, v95
	v_fmac_f32_e32 v82, v96, v96
	v_fmac_f32_e32 v83, v94, v94
	v_pk_mul_f32 v[110:111], v[98:99], v[110:111] op_sel_hi:[0,1]
	v_add_f32_e32 v82, v82, v83
	v_mul_f32_e32 v83, v93, v93
	v_mul_f32_e32 v98, v91, v91
	v_fmac_f32_e32 v83, v92, v92
	v_fmac_f32_e32 v98, v90, v90
	v_add_f32_e32 v83, v83, v98
	v_add_f32_e32 v82, v82, v83
	v_mul_f32_e32 v83, v109, v109
	v_mul_f32_e32 v98, v87, v87
	v_fmac_f32_e32 v83, v108, v108
	v_fmac_f32_e32 v98, v86, v86
	v_pk_fma_f32 v[88:89], v[12:13], v[110:111], v[88:89]
	v_add_f32_e32 v83, v83, v98
	v_add_f32_e32 v82, v83, v82
	v_mul_f32_e32 v83, v89, v89
	v_mul_f32_e32 v98, v85, v85
	v_fmac_f32_e32 v83, v88, v88
	v_fmac_f32_e32 v98, v84, v84
	v_add_f32_e32 v83, v83, v98
	v_add_f32_e32 v82, v83, v82
	s_nop 0
	v_bfe_u32 v98, v96, 16, 1
	v_add3_u32 v96, v96, v98, s37
	v_bfe_u32 v98, v97, 16, 1
	v_lshrrev_b32_e32 v96, 16, v96
	s_waitcnt lgkmcnt(0)
; __device__ __forceinline__ float shx(float v, int m, int lane) { return __builtin_bit_cast(float, __builtin_amdgcn_ds_bpermute((lane ^ m) << 2, __builtin_bit_cast(int, v))); }
; __device__ __forceinline__ unsigned pk2(float lo, float hi) { return f2bf(lo) | (f2bf(hi) << 16); }
; template <int RB> __device__ __forceinline__ void res_phase(float* xout, const bf16_t* mix, const float* ssp, const float* gain, bf16_t* XN, float* rinv, int gw, int ngw, int lane) {
;     ...
;         for (int i = 0; i < RB; ++i) { const int row = row0 + i; float p = ps[i];
;             p += shx(p, 1, lane); p += shx(p, 2, lane); p += shx(p, 4, lane); p += shx(p, 8, lane);
;             const float rm = 1.0f / sqrtf(p * (1.0f / DM) + EPS);
;             f32x4 v[4]; float s = 0.f;
; #pragma unroll
;             for (int j = 0; j < 4; ++j) { const u32x2 a = xw[i][j], m = mw[i][j];
;                 f32x4 xv; xv[0] = __builtin_bit_cast(float, a.x << 16); xv[1] = __builtin_bit_cast(float, a.x & 0xffff0000u); xv[2] = __builtin_bit_cast(float, a.y << 16); xv[3] = __builtin_bit_cast(float, a.y & 0xffff0000u);
;                 f32x4 mv; mv[0] = __builtin_bit_cast(float, m.x << 16); mv[1] = __builtin_bit_cast(float, m.x & 0xffff0000u); mv[2] = __builtin_bit_cast(float, m.y << 16); mv[3] = __builtin_bit_cast(float, m.y & 0xffff0000u);
;                 v[j] = xv + mv * rm * gv[j]; s += (v[j][0] * v[j][0] + v[j][1] * v[j][1]) + (v[j][2] * v[j][2] + v[j][3] * v[j][3]); }
;             if (xout) { f32x4* xo = (f32x4*)(xout + (size_t)row * DM) + lane;
; #pragma unroll
;                 for (int j = 0; j < 4; ++j) xo[64 * j] = v[j];
;             } else {
;                 s = wave_sum(s, lane); u32x2* xr = (u32x2*)(XN + (size_t)row * DM) + lane;
; #pragma unroll
;                 for (int j = 0; j < 4; ++j) { u32x2 w; w.x = pk2(v[j][0], v[j][1]); w.y = pk2(v[j][2], v[j][3]); xr[64 * j] = w; }
;                 if (lane == 0) rinv[row] = 1.0f / sqrtf(s * (1.0f / DM) + EPS);
	s_nop 1
	v_add_f32_dpp v82, v82, v82 quad_perm:[1,0,3,2] row_mask:0xf bank_mask:0xf
	s_nop 0
	v_add3_u32 v97, v97, v98, s37
	v_and_or_b32 v96, v97, s57, v96
	v_bfe_u32 v97, v94, 16, 1
	v_add3_u32 v94, v94, v97, s37
	s_waitcnt lgkmcnt(0)
	s_nop 1
	v_add_f32_dpp v82, v82, v82 quad_perm:[2,3,0,1] row_mask:0xf bank_mask:0xf
	s_nop 0
	v_bfe_u32 v97, v95, 16, 1
	v_lshrrev_b32_e32 v94, 16, v94
	v_add3_u32 v95, v95, v97, s37
	v_and_or_b32 v97, v95, s57, v94
	v_bfe_u32 v94, v92, 16, 1
	s_waitcnt lgkmcnt(0)
	s_nop 1
	v_add_f32_dpp v82, v82, v82 row_half_mirror row_mask:0xf bank_mask:0xf
	v_add3_u32 v92, v92, v94, s37
	v_bfe_u32 v94, v93, 16, 1
	s_nop 0
	v_lshrrev_b32_e32 v92, 16, v92
	v_add3_u32 v93, v93, v94, s37
	v_and_or_b32 v92, v93, s57, v92
	v_bfe_u32 v93, v90, 16, 1
	v_add3_u32 v90, v90, v93, s37
	v_bfe_u32 v93, v91, 16, 1
	v_lshrrev_b32_e32 v90, 16, v90
	v_add3_u32 v91, v91, v93, s37
	v_and_or_b32 v93, v91, s57, v90
	v_bfe_u32 v90, v108, 16, 1
	s_waitcnt lgkmcnt(0)
	s_nop 1
	v_add_f32_dpp v82, v82, v82 row_mirror row_mask:0xf bank_mask:0xf
	v_add3_u32 v90, v108, v90, s37
	v_bfe_u32 v91, v109, 16, 1
	ds_bpermute_b32 v83, v103, v82
	v_lshrrev_b32_e32 v90, 16, v90
	v_add3_u32 v91, v109, v91, s37
	v_and_or_b32 v90, v91, s57, v90
	v_bfe_u32 v91, v86, 16, 1
	v_add3_u32 v86, v86, v91, s37
	v_bfe_u32 v91, v87, 16, 1
	v_lshrrev_b32_e32 v86, 16, v86
	v_add3_u32 v87, v87, v91, s37
	v_and_or_b32 v91, v87, s57, v86
	v_bfe_u32 v86, v88, 16, 1
	s_waitcnt lgkmcnt(0)
	v_add_f32_e32 v82, v82, v83
	v_add3_u32 v86, v88, v86, s37
	v_bfe_u32 v87, v89, 16, 1
	ds_bpermute_b32 v83, v104, v82
	v_lshrrev_b32_e32 v86, 16, v86
	v_add3_u32 v87, v89, v87, s37
	v_and_or_b32 v86, v87, s57, v86
	v_bfe_u32 v87, v84, 16, 1
	v_add3_u32 v84, v84, v87, s37
	v_bfe_u32 v87, v85, 16, 1
	v_lshrrev_b32_e32 v84, 16, v84
	v_add3_u32 v85, v85, v87, s37
	v_and_or_b32 v87, v85, s57, v84
	flat_store_dwordx2 v[80:81], v[96:97]
	flat_store_dwordx2 v[80:81], v[92:93] offset:512
	flat_store_dwordx2 v[80:81], v[90:91] offset:1024
	flat_store_dwordx2 v[80:81], v[86:87] offset:1536
	s_and_saveexec_b64 s[82:83], s[38:39]
	s_cbranch_execz .LBB0_469
	s_waitcnt lgkmcnt(0)
	v_add_f32_e32 v80, v82, v83
	v_fmamk_f32 v80, v80, 0x3a800000, v217
	v_mul_f32_e32 v81, 0x4f800000, v80
	v_cmp_gt_f32_e32 vcc, s59, v80
	s_add_u32 s3, s0, s70
	s_addc_u32 s7, s1, s71
	v_cndmask_b32_e32 v80, v80, v81, vcc
	v_sqrt_f32_e32 v81, v80
	s_nop 0
	v_add_u32_e32 v82, -1, v81
	v_fma_f32 v84, -v82, v81, v80
	v_add_u32_e32 v83, 1, v81
	v_cmp_ge_f32_e64 s[40:41], 0, v84
	s_nop 1
	v_cndmask_b32_e64 v82, v81, v82, s[40:41]
	v_fma_f32 v81, -v83, v81, v80
	v_cmp_lt_f32_e64 s[40:41], 0, v81
	s_nop 1
	v_cndmask_b32_e64 v81, v82, v83, s[40:41]
	v_mul_f32_e32 v82, 0x37800000, v81
	v_cndmask_b32_e32 v81, v81, v82, vcc
	v_cmp_class_f32_e32 vcc, v80, v218
	s_nop 1
	v_cndmask_b32_e32 v80, v81, v80, vcc
	v_div_scale_f32 v81, s[10:11], v80, v80, 1.0
	v_rcp_f32_e32 v82, v81
	s_nop 0
	v_fma_f32 v83, -v81, v82, 1.0
	v_fmac_f32_e32 v82, v83, v82
	v_div_scale_f32 v83, vcc, 1.0, v80, 1.0
	v_mul_f32_e32 v84, v83, v82
	v_fma_f32 v85, -v81, v84, v83
	v_fmac_f32_e32 v84, v85, v82
	v_fma_f32 v81, -v81, v84, v83
	v_div_fmas_f32 v81, v81, v82, v84
	v_div_fixup_f32 v82, v81, v80, 1.0
	v_mov_b32_e32 v80, s3
	v_add_co_u32_e32 v80, vcc, 0x300000, v80
	v_mov_b32_e32 v81, s7
	s_nop 0
	v_addc_co_u32_e32 v81, vcc, 0, v81, vcc
	flat_store_dword v[80:81], v82
.LBB0_469:
	s_or_b64 exec, exec, s[82:83]
	s_nop 0
	s_waitcnt lgkmcnt(0)
	s_nop 1
	v_add_f32_dpp v80, v107, v107 quad_perm:[1,0,3,2] row_mask:0xf bank_mask:0xf
	s_nop 0
	s_waitcnt lgkmcnt(0)
	s_nop 1
	v_add_f32_dpp v82, v80, v80 quad_perm:[2,3,0,1] row_mask:0xf bank_mask:0xf
	s_nop 0
	v_lshlrev_b32_e32 v80, 16, v78
	v_and_b32_e32 v81, 0xffff0000, v78
	v_lshlrev_b32_e32 v78, 16, v79
	v_and_b32_e32 v79, 0xffff0000, v79
	s_waitcnt lgkmcnt(0)
	s_nop 1
	v_add_f32_dpp v84, v82, v82 row_half_mirror row_mask:0xf bank_mask:0xf
	s_nop 0
	v_lshlrev_b32_e32 v82, 16, v76
	v_and_b32_e32 v83, 0xffff0000, v76
	s_waitcnt lgkmcnt(0)
	s_nop 1
	v_add_f32_dpp v76, v84, v84 row_mirror row_mask:0xf bank_mask:0xf
	v_fmamk_f32 v76, v76, 0x3a800000, v217
	v_mul_f32_e32 v84, 0x4f800000, v76
	v_cmp_gt_f32_e32 vcc, s59, v76
	s_nop 1
	v_cndmask_b32_e32 v85, v76, v84, vcc
	v_sqrt_f32_e32 v86, v85
	v_lshlrev_b32_e32 v84, 16, v74
	v_lshlrev_b32_e32 v76, 16, v77
	v_and_b32_e32 v77, 0xffff0000, v77
	v_add_u32_e32 v87, -1, v86
	v_add_u32_e32 v88, 1, v86
	v_fma_f32 v89, -v87, v86, v85
	v_fma_f32 v90, -v88, v86, v85
	v_cmp_ge_f32_e64 s[40:41], 0, v89
	s_nop 1
	v_cndmask_b32_e64 v86, v86, v87, s[40:41]
	v_cmp_lt_f32_e64 s[40:41], 0, v90
	s_nop 1
	v_cndmask_b32_e64 v86, v86, v88, s[40:41]
	v_mul_f32_e32 v87, 0x37800000, v86
	v_cndmask_b32_e32 v86, v86, v87, vcc
	v_cmp_class_f32_e32 vcc, v85, v218
	s_nop 1
	v_cndmask_b32_e32 v86, v86, v85, vcc
	v_div_scale_f32 v87, s[10:11], v86, v86, 1.0
	v_rcp_f32_e32 v88, v87
	v_and_b32_e32 v85, 0xffff0000, v74
	v_div_scale_f32 v74, vcc, 1.0, v86, 1.0
	v_fma_f32 v89, -v87, v88, 1.0
	v_fmac_f32_e32 v88, v89, v88
	v_mul_f32_e32 v89, v74, v88
	v_fma_f32 v90, -v87, v89, v74
	v_fmac_f32_e32 v89, v90, v88
	v_fma_f32 v74, -v87, v89, v74
	v_div_fmas_f32 v74, v74, v88, v89
	v_div_fixup_f32 v74, v74, v86, 1.0
	v_pk_mul_f32 v[82:83], v[74:75], v[82:83] op_sel_hi:[0,1]
	v_pk_fma_f32 v[80:81], v[0:1], v[82:83], v[80:81]
	v_lshlrev_b32_e32 v82, 16, v72
	v_and_b32_e32 v83, 0xffff0000, v72
	v_pk_mul_f32 v[76:77], v[74:75], v[76:77] op_sel_hi:[0,1]
	v_lshlrev_b32_e32 v72, 16, v73
	v_and_b32_e32 v73, 0xffff0000, v73
	v_pk_mul_f32 v[82:83], v[74:75], v[82:83] op_sel_hi:[0,1]
	v_pk_fma_f32 v[76:77], v[2:3], v[76:77], v[78:79]
; __device__ __forceinline__ unsigned pk2(float lo, float hi) { return f2bf(lo) | (f2bf(hi) << 16); }
; template <int RB> __device__ __forceinline__ void res_phase(float* xout, const bf16_t* mix, const float* ssp, const float* gain, bf16_t* XN, float* rinv, int gw, int ngw, int lane) {
;     ...
;             f32x4 v[4]; float s = 0.f;
; #pragma unroll
;             for (int j = 0; j < 4; ++j) { const u32x2 a = xw[i][j], m = mw[i][j];
;                 f32x4 xv; xv[0] = __builtin_bit_cast(float, a.x << 16); xv[1] = __builtin_bit_cast(float, a.x & 0xffff0000u); xv[2] = __builtin_bit_cast(float, a.y << 16); xv[3] = __builtin_bit_cast(float, a.y & 0xffff0000u);
;                 f32x4 mv; mv[0] = __builtin_bit_cast(float, m.x << 16); mv[1] = __builtin_bit_cast(float, m.x & 0xffff0000u); mv[2] = __builtin_bit_cast(float, m.y << 16); mv[3] = __builtin_bit_cast(float, m.y & 0xffff0000u);
;                 v[j] = xv + mv * rm * gv[j]; s += (v[j][0] * v[j][0] + v[j][1] * v[j][1]) + (v[j][2] * v[j][2] + v[j][3] * v[j][3]); }
;             if (xout) { f32x4* xo = (f32x4*)(xout + (size_t)row * DM) + lane;
; #pragma unroll
;                 for (int j = 0; j < 4; ++j) xo[64 * j] = v[j];
;             } else {
;                 s = wave_sum(s, lane); u32x2* xr = (u32x2*)(XN + (size_t)row * DM) + lane;
; #pragma unroll
;                 for (int j = 0; j < 4; ++j) { u32x2 w; w.x = pk2(v[j][0], v[j][1]); w.y = pk2(v[j][2], v[j][3]); xr[64 * j] = w; }
;                 if (lane == 0) rinv[row] = 1.0f / sqrtf(s * (1.0f / DM) + EPS);
	v_lshlrev_b32_e32 v78, 16, v75
	v_and_b32_e32 v79, 0xffff0000, v75
	v_pk_mul_f32 v[72:73], v[74:75], v[72:73] op_sel_hi:[0,1]
	v_pk_fma_f32 v[82:83], v[4:5], v[82:83], v[84:85]
	v_lshlrev_b32_e32 v84, 16, v68
	v_and_b32_e32 v85, 0xffff0000, v68
	v_pk_fma_f32 v[72:73], v[6:7], v[72:73], v[78:79]
	v_lshlrev_b32_e32 v78, 16, v70
	v_and_b32_e32 v79, 0xffff0000, v70
	v_lshlrev_b32_e32 v68, 16, v69
	v_and_b32_e32 v69, 0xffff0000, v69
	v_pk_mul_f32 v[84:85], v[74:75], v[84:85] op_sel_hi:[0,1]
	v_lshlrev_b32_e32 v70, 16, v71
	v_and_b32_e32 v71, 0xffff0000, v71
	v_pk_mul_f32 v[68:69], v[74:75], v[68:69] op_sel_hi:[0,1]
	v_pk_fma_f32 v[78:79], v[8:9], v[84:85], v[78:79]
	v_lshlrev_b32_e32 v84, 16, v64
	v_and_b32_e32 v85, 0xffff0000, v64
	v_lshlrev_b32_e32 v64, 16, v65
	v_and_b32_e32 v65, 0xffff0000, v65
	v_pk_fma_f32 v[68:69], v[10:11], v[68:69], v[70:71]
	v_lshlrev_b32_e32 v70, 16, v66
	v_and_b32_e32 v71, 0xffff0000, v66
	v_lshlrev_b32_e32 v66, 16, v67
	v_and_b32_e32 v67, 0xffff0000, v67
	v_pk_mul_f32 v[64:65], v[74:75], v[64:65] op_sel_hi:[0,1]
	v_pk_fma_f32 v[64:65], v[14:15], v[64:65], v[66:67]
	v_mul_f32_e32 v66, v81, v81
	v_mul_f32_e32 v67, v77, v77
	v_pk_mul_f32 v[74:75], v[74:75], v[84:85] op_sel_hi:[0,1]
	v_fmac_f32_e32 v66, v80, v80
	v_fmac_f32_e32 v67, v76, v76
	v_pk_fma_f32 v[70:71], v[12:13], v[74:75], v[70:71]
	v_add_f32_e32 v66, v66, v67
	v_mul_f32_e32 v67, v83, v83
	v_mul_f32_e32 v74, v73, v73
	v_fmac_f32_e32 v67, v82, v82
	v_fmac_f32_e32 v74, v72, v72
	v_add_f32_e32 v67, v67, v74
	v_add_f32_e32 v66, v66, v67
	v_mul_f32_e32 v67, v79, v79
	v_mul_f32_e32 v74, v69, v69
	v_fmac_f32_e32 v67, v78, v78
	v_fmac_f32_e32 v74, v68, v68
	v_add_f32_e32 v67, v67, v74
	v_add_f32_e32 v66, v67, v66
	v_mul_f32_e32 v67, v71, v71
	v_mul_f32_e32 v74, v65, v65
	v_fmac_f32_e32 v67, v70, v70
	v_fmac_f32_e32 v74, v64, v64
	v_add_f32_e32 v67, v67, v74
	v_add_f32_e32 v66, v67, v66
	s_nop 0
	s_mov_b64 s[10:11], 0x3800800
	s_waitcnt lgkmcnt(0)
	s_nop 1
	v_add_f32_dpp v66, v66, v66 quad_perm:[1,0,3,2] row_mask:0xf bank_mask:0xf
	s_nop 0
	s_waitcnt lgkmcnt(0)
	s_nop 1
	v_add_f32_dpp v66, v66, v66 quad_perm:[2,3,0,1] row_mask:0xf bank_mask:0xf
	s_nop 0
	s_waitcnt lgkmcnt(0)
	s_nop 1
	v_add_f32_dpp v66, v66, v66 row_half_mirror row_mask:0xf bank_mask:0xf
	s_nop 0
	s_waitcnt lgkmcnt(0)
	s_nop 1
	v_add_f32_dpp v88, v66, v66 row_mirror row_mask:0xf bank_mask:0xf
	ds_bpermute_b32 v89, v103, v88
	v_lshl_add_u64 v[66:67], v[62:63], 0, s[10:11]
	s_mov_b64 s[10:11], 0x3800a00
	v_lshl_add_u64 v[74:75], v[62:63], 0, s[10:11]
	s_mov_b64 s[10:11], 0x3800c00
	v_lshl_add_u64 v[84:85], v[62:63], 0, s[10:11]
	s_mov_b64 s[10:11], 0x3800e00
	v_lshl_add_u64 v[86:87], v[62:63], 0, s[10:11]
	s_waitcnt lgkmcnt(0)
	v_add_f32_e32 v62, v88, v89
	v_bfe_u32 v88, v80, 16, 1
	v_add3_u32 v80, v80, v88, s37
	v_bfe_u32 v88, v81, 16, 1
	v_lshrrev_b32_e32 v80, 16, v80
	v_add3_u32 v81, v81, v88, s37
	v_and_or_b32 v80, v81, s57, v80
	v_bfe_u32 v81, v76, 16, 1
	v_add3_u32 v76, v76, v81, s37
	v_bfe_u32 v81, v77, 16, 1
	v_lshrrev_b32_e32 v76, 16, v76
	v_add3_u32 v77, v77, v81, s37
	v_and_or_b32 v81, v77, s57, v76
	flat_store_dwordx2 v[66:67], v[80:81]
	v_bfe_u32 v66, v82, 16, 1
	v_add3_u32 v66, v82, v66, s37
	v_bfe_u32 v67, v83, 16, 1
	v_lshrrev_b32_e32 v66, 16, v66
	v_add3_u32 v67, v83, v67, s37
	v_and_or_b32 v66, v67, s57, v66
	v_bfe_u32 v67, v72, 16, 1
	v_add3_u32 v67, v72, v67, s37
	v_bfe_u32 v72, v73, 16, 1
	v_lshrrev_b32_e32 v67, 16, v67
	v_add3_u32 v72, v73, v72, s37
	v_and_or_b32 v67, v72, s57, v67
	flat_store_dwordx2 v[74:75], v[66:67]
	v_bfe_u32 v66, v78, 16, 1
	v_add3_u32 v66, v78, v66, s37
	v_bfe_u32 v67, v79, 16, 1
	v_lshrrev_b32_e32 v66, 16, v66
	v_add3_u32 v67, v79, v67, s37
	v_and_or_b32 v66, v67, s57, v66
	v_bfe_u32 v67, v68, 16, 1
	v_add3_u32 v67, v68, v67, s37
	v_bfe_u32 v68, v69, 16, 1
	v_lshrrev_b32_e32 v67, 16, v67
	v_add3_u32 v68, v69, v68, s37
	v_and_or_b32 v67, v68, s57, v67
	flat_store_dwordx2 v[84:85], v[66:67]
	v_bfe_u32 v66, v70, 16, 1
	v_add3_u32 v66, v70, v66, s37
	v_bfe_u32 v67, v71, 16, 1
	ds_bpermute_b32 v63, v104, v62
	v_lshrrev_b32_e32 v66, 16, v66
	v_add3_u32 v67, v71, v67, s37
	v_and_or_b32 v66, v67, s57, v66
	v_bfe_u32 v67, v64, 16, 1
	v_add3_u32 v64, v64, v67, s37
	v_bfe_u32 v67, v65, 16, 1
	v_lshrrev_b32_e32 v64, 16, v64
	v_add3_u32 v65, v65, v67, s37
	v_and_or_b32 v67, v65, s57, v64
	flat_store_dwordx2 v[86:87], v[66:67]
	s_and_saveexec_b64 s[82:83], s[38:39]
	s_cbranch_execz .LBB0_471
	s_waitcnt lgkmcnt(0)
	v_add_f32_e32 v62, v62, v63
	v_fmamk_f32 v62, v62, 0x3a800000, v217
	v_mul_f32_e32 v63, 0x4f800000, v62
	v_cmp_gt_f32_e32 vcc, s59, v62
	s_add_u32 s3, s0, s70
	s_addc_u32 s7, s1, s71
	v_cndmask_b32_e32 v62, v62, v63, vcc
	v_sqrt_f32_e32 v63, v62
	s_nop 0
	v_add_u32_e32 v64, -1, v63
	v_fma_f32 v66, -v64, v63, v62
	v_add_u32_e32 v65, 1, v63
	v_cmp_ge_f32_e64 s[40:41], 0, v66
	s_nop 1
	v_cndmask_b32_e64 v64, v63, v64, s[40:41]
	v_fma_f32 v63, -v65, v63, v62
	v_cmp_lt_f32_e64 s[40:41], 0, v63
	s_nop 1
	v_cndmask_b32_e64 v63, v64, v65, s[40:41]
	v_mul_f32_e32 v64, 0x37800000, v63
	v_cndmask_b32_e32 v63, v63, v64, vcc
	v_cmp_class_f32_e32 vcc, v62, v218
	s_nop 1
	v_cndmask_b32_e32 v62, v63, v62, vcc
	v_div_scale_f32 v63, s[10:11], v62, v62, 1.0
	v_rcp_f32_e32 v64, v63
	s_nop 0
	v_fma_f32 v65, -v63, v64, 1.0
	v_fmac_f32_e32 v64, v65, v64
	v_div_scale_f32 v65, vcc, 1.0, v62, 1.0
	v_mul_f32_e32 v66, v65, v64
	v_fma_f32 v67, -v63, v66, v65
	v_fmac_f32_e32 v66, v67, v64
	v_fma_f32 v63, -v63, v66, v65
	v_div_fmas_f32 v63, v63, v64, v66
	v_div_fixup_f32 v64, v63, v62, 1.0
	v_mov_b32_e32 v62, s3
	v_add_co_u32_e32 v62, vcc, 0x300000, v62
	v_mov_b32_e32 v63, s7
	s_nop 0
	v_addc_co_u32_e32 v63, vcc, 0, v63, vcc
	flat_store_dword v[62:63], v64 offset:4
; __device__ __forceinline__ float shx(float v, int m, int lane) { return __builtin_bit_cast(float, __builtin_amdgcn_ds_bpermute((lane ^ m) << 2, __builtin_bit_cast(int, v))); }
; __device__ __forceinline__ unsigned pk2(float lo, float hi) { return f2bf(lo) | (f2bf(hi) << 16); }
; template <int RB> __device__ __forceinline__ void res_phase(float* xout, const bf16_t* mix, const float* ssp, const float* gain, bf16_t* XN, float* rinv, int gw, int ngw, int lane) {
;     ...
;         for (int i = 0; i < RB; ++i) { const int row = row0 + i; float p = ps[i];
;             p += shx(p, 1, lane); p += shx(p, 2, lane); p += shx(p, 4, lane); p += shx(p, 8, lane);
;             const float rm = 1.0f / sqrtf(p * (1.0f / DM) + EPS);
;             f32x4 v[4]; float s = 0.f;
; #pragma unroll
;             for (int j = 0; j < 4; ++j) { const u32x2 a = xw[i][j], m = mw[i][j];
;                 f32x4 xv; xv[0] = __builtin_bit_cast(float, a.x << 16); xv[1] = __builtin_bit_cast(float, a.x & 0xffff0000u); xv[2] = __builtin_bit_cast(float, a.y << 16); xv[3] = __builtin_bit_cast(float, a.y & 0xffff0000u);
;                 f32x4 mv; mv[0] = __builtin_bit_cast(float, m.x << 16); mv[1] = __builtin_bit_cast(float, m.x & 0xffff0000u); mv[2] = __builtin_bit_cast(float, m.y << 16); mv[3] = __builtin_bit_cast(float, m.y & 0xffff0000u);
;                 v[j] = xv + mv * rm * gv[j]; s += (v[j][0] * v[j][0] + v[j][1] * v[j][1]) + (v[j][2] * v[j][2] + v[j][3] * v[j][3]); }
;             if (xout) { f32x4* xo = (f32x4*)(xout + (size_t)row * DM) + lane;
; #pragma unroll
;                 for (int j = 0; j < 4; ++j) xo[64 * j] = v[j];
;             } else {
;                 s = wave_sum(s, lane); u32x2* xr = (u32x2*)(XN + (size_t)row * DM) + lane;
; #pragma unroll
;                 for (int j = 0; j < 4; ++j) { u32x2 w; w.x = pk2(v[j][0], v[j][1]); w.y = pk2(v[j][2], v[j][3]); xr[64 * j] = w; }
;                 if (lane == 0) rinv[row] = 1.0f / sqrtf(s * (1.0f / DM) + EPS);
.LBB0_471:
	s_or_b64 exec, exec, s[82:83]
	s_nop 0
	s_waitcnt lgkmcnt(0)
	s_nop 1
	v_add_f32_dpp v62, v106, v106 quad_perm:[1,0,3,2] row_mask:0xf bank_mask:0xf
	s_nop 0
	s_waitcnt lgkmcnt(0)
	s_nop 1
	v_add_f32_dpp v62, v62, v62 quad_perm:[2,3,0,1] row_mask:0xf bank_mask:0xf
	s_nop 0
	s_waitcnt lgkmcnt(0)
	s_nop 1
	v_add_f32_dpp v62, v62, v62 row_half_mirror row_mask:0xf bank_mask:0xf
	s_nop 0
	s_waitcnt lgkmcnt(0)
	s_nop 1
	v_add_f32_dpp v62, v62, v62 row_mirror row_mask:0xf bank_mask:0xf
	v_fmamk_f32 v62, v62, 0x3a800000, v217
	v_cmp_gt_f32_e32 vcc, s59, v62
	v_mul_f32_e32 v63, 0x4f800000, v62
	s_nop 0
	v_cndmask_b32_e32 v62, v62, v63, vcc
	v_sqrt_f32_e32 v63, v62
	s_nop 0
	v_add_u32_e32 v64, -1, v63
	v_fma_f32 v65, -v64, v63, v62
	v_cmp_ge_f32_e64 s[40:41], 0, v65
	v_add_u32_e32 v65, 1, v63
	s_nop 0
	v_cndmask_b32_e64 v64, v63, v64, s[40:41]
	v_fma_f32 v63, -v65, v63, v62
	v_cmp_lt_f32_e64 s[40:41], 0, v63
	s_nop 1
	v_cndmask_b32_e64 v63, v64, v65, s[40:41]
	v_mul_f32_e32 v64, 0x37800000, v63
	v_cndmask_b32_e32 v63, v63, v64, vcc
	v_cmp_class_f32_e32 vcc, v62, v218
	s_nop 1
	v_cndmask_b32_e32 v62, v63, v62, vcc
	v_div_scale_f32 v63, s[10:11], v62, v62, 1.0
	v_rcp_f32_e32 v64, v63
	s_nop 0
	v_fma_f32 v65, -v63, v64, 1.0
	v_fmac_f32_e32 v64, v65, v64
	v_div_scale_f32 v65, vcc, 1.0, v62, 1.0
	v_mul_f32_e32 v66, v65, v64
	v_fma_f32 v67, -v63, v66, v65
	v_fmac_f32_e32 v66, v67, v64
	v_fma_f32 v63, -v63, v66, v65
	v_div_fmas_f32 v63, v63, v64, v66
	v_div_fixup_f32 v62, v63, v62, 1.0
	v_lshlrev_b32_e32 v64, 16, v60
	v_and_b32_e32 v65, 0xffff0000, v60
	v_lshlrev_b32_e32 v66, 16, v61
	v_and_b32_e32 v67, 0xffff0000, v61
	v_lshlrev_b32_e32 v60, 16, v58
	v_and_b32_e32 v61, 0xffff0000, v58
	v_lshlrev_b32_e32 v58, 16, v59
	v_and_b32_e32 v59, 0xffff0000, v59
	v_pk_mul_f32 v[58:59], v[62:63], v[58:59] op_sel_hi:[0,1]
	v_pk_mul_f32 v[60:61], v[62:63], v[60:61] op_sel_hi:[0,1]
	v_pk_fma_f32 v[58:59], v[2:3], v[58:59], v[66:67]
	v_lshlrev_b32_e32 v66, 16, v54
	v_and_b32_e32 v67, 0xffff0000, v54
	v_pk_fma_f32 v[60:61], v[0:1], v[60:61], v[64:65]
	v_lshlrev_b32_e32 v64, 16, v56
	v_and_b32_e32 v65, 0xffff0000, v56
	v_lshlrev_b32_e32 v54, 16, v55
	v_and_b32_e32 v55, 0xffff0000, v55
	v_pk_mul_f32 v[66:67], v[62:63], v[66:67] op_sel_hi:[0,1]
	v_lshlrev_b32_e32 v56, 16, v57
	v_and_b32_e32 v57, 0xffff0000, v57
	v_pk_mul_f32 v[54:55], v[62:63], v[54:55] op_sel_hi:[0,1]
	v_pk_fma_f32 v[64:65], v[4:5], v[66:67], v[64:65]
	v_lshlrev_b32_e32 v66, 16, v50
	v_and_b32_e32 v67, 0xffff0000, v50
	v_pk_fma_f32 v[54:55], v[6:7], v[54:55], v[56:57]
	v_lshlrev_b32_e32 v56, 16, v52
	v_and_b32_e32 v57, 0xffff0000, v52
	v_lshlrev_b32_e32 v50, 16, v51
	v_and_b32_e32 v51, 0xffff0000, v51
	v_pk_mul_f32 v[66:67], v[62:63], v[66:67] op_sel_hi:[0,1]
	v_lshlrev_b32_e32 v52, 16, v53
	v_and_b32_e32 v53, 0xffff0000, v53
	v_pk_mul_f32 v[50:51], v[62:63], v[50:51] op_sel_hi:[0,1]
	v_pk_fma_f32 v[56:57], v[8:9], v[66:67], v[56:57]
	v_lshlrev_b32_e32 v66, 16, v46
	v_and_b32_e32 v67, 0xffff0000, v46
	v_lshlrev_b32_e32 v46, 16, v47
	v_and_b32_e32 v47, 0xffff0000, v47
	v_pk_fma_f32 v[50:51], v[10:11], v[50:51], v[52:53]
	v_lshlrev_b32_e32 v52, 16, v48
	v_and_b32_e32 v53, 0xffff0000, v48
	v_lshlrev_b32_e32 v48, 16, v49
	v_and_b32_e32 v49, 0xffff0000, v49
	v_pk_mul_f32 v[46:47], v[62:63], v[46:47] op_sel_hi:[0,1]
	v_pk_fma_f32 v[48:49], v[14:15], v[46:47], v[48:49]
	v_mul_f32_e32 v46, v61, v61
	v_mul_f32_e32 v47, v59, v59
	v_pk_mul_f32 v[62:63], v[62:63], v[66:67] op_sel_hi:[0,1]
	v_fmac_f32_e32 v46, v60, v60
	v_fmac_f32_e32 v47, v58, v58
	v_pk_fma_f32 v[52:53], v[12:13], v[62:63], v[52:53]
	v_add_f32_e32 v46, v46, v47
	v_mul_f32_e32 v47, v65, v65
	v_mul_f32_e32 v62, v55, v55
	v_fmac_f32_e32 v47, v64, v64
	v_fmac_f32_e32 v62, v54, v54
	v_add_f32_e32 v47, v47, v62
	v_add_f32_e32 v46, v46, v47
	v_mul_f32_e32 v47, v57, v57
	v_mul_f32_e32 v62, v51, v51
	v_fmac_f32_e32 v47, v56, v56
	v_fmac_f32_e32 v62, v50, v50
	v_add_f32_e32 v47, v47, v62
	v_add_f32_e32 v46, v47, v46
	v_mul_f32_e32 v47, v53, v53
	v_mul_f32_e32 v62, v49, v49
	v_fmac_f32_e32 v47, v52, v52
	v_fmac_f32_e32 v62, v48, v48
	v_add_f32_e32 v47, v47, v62
	v_add_f32_e32 v46, v47, v46
	s_nop 0
	v_bfe_u32 v62, v60, 16, 1
	v_add3_u32 v60, v60, v62, s37
	v_bfe_u32 v62, v61, 16, 1
	v_lshrrev_b32_e32 v60, 16, v60
	s_waitcnt lgkmcnt(0)
	s_nop 1
	v_add_f32_dpp v46, v46, v46 quad_perm:[1,0,3,2] row_mask:0xf bank_mask:0xf
	s_nop 0
	v_add3_u32 v61, v61, v62, s37
	v_and_or_b32 v60, v61, s57, v60
	v_bfe_u32 v61, v58, 16, 1
	v_add3_u32 v58, v58, v61, s37
	s_waitcnt lgkmcnt(0)
	s_nop 1
	v_add_f32_dpp v46, v46, v46 quad_perm:[2,3,0,1] row_mask:0xf bank_mask:0xf
	s_nop 0
	v_bfe_u32 v61, v59, 16, 1
	v_lshrrev_b32_e32 v58, 16, v58
	v_add3_u32 v59, v59, v61, s37
	v_and_or_b32 v61, v59, s57, v58
	v_bfe_u32 v58, v64, 16, 1
	s_waitcnt lgkmcnt(0)
	s_nop 1
	v_add_f32_dpp v46, v46, v46 row_half_mirror row_mask:0xf bank_mask:0xf
	v_add3_u32 v58, v64, v58, s37
	v_bfe_u32 v59, v65, 16, 1
	s_nop 0
	v_lshrrev_b32_e32 v58, 16, v58
	v_add3_u32 v59, v65, v59, s37
	v_and_or_b32 v58, v59, s57, v58
	v_bfe_u32 v59, v54, 16, 1
	v_add3_u32 v54, v54, v59, s37
	v_bfe_u32 v59, v55, 16, 1
	v_lshrrev_b32_e32 v54, 16, v54
	v_add3_u32 v55, v55, v59, s37
	v_and_or_b32 v59, v55, s57, v54
	v_bfe_u32 v54, v56, 16, 1
	s_waitcnt lgkmcnt(0)
	s_nop 1
	v_add_f32_dpp v46, v46, v46 row_mirror row_mask:0xf bank_mask:0xf
	v_add3_u32 v54, v56, v54, s37
	v_bfe_u32 v55, v57, 16, 1
	ds_bpermute_b32 v47, v103, v46
	v_lshrrev_b32_e32 v54, 16, v54
	v_add3_u32 v55, v57, v55, s37
	v_and_or_b32 v54, v55, s57, v54
	v_bfe_u32 v55, v50, 16, 1
	v_add3_u32 v50, v50, v55, s37
	v_bfe_u32 v55, v51, 16, 1
	v_lshrrev_b32_e32 v50, 16, v50
	v_add3_u32 v51, v51, v55, s37
	v_and_or_b32 v55, v51, s57, v50
	v_bfe_u32 v50, v52, 16, 1
	s_waitcnt lgkmcnt(0)
	v_add_f32_e32 v46, v46, v47
	v_add3_u32 v50, v52, v50, s37
	v_bfe_u32 v51, v53, 16, 1
	ds_bpermute_b32 v47, v104, v46
	v_lshrrev_b32_e32 v50, 16, v50
	v_add3_u32 v51, v53, v51, s37
	v_and_or_b32 v50, v51, s57, v50
	v_bfe_u32 v51, v48, 16, 1
	v_add3_u32 v48, v48, v51, s37
	v_bfe_u32 v51, v49, 16, 1
	v_lshrrev_b32_e32 v48, 16, v48
	v_add3_u32 v49, v49, v51, s37
	v_and_or_b32 v51, v49, s57, v48
	flat_store_dwordx2 v[44:45], v[60:61]
	flat_store_dwordx2 v[44:45], v[58:59] offset:512
	flat_store_dwordx2 v[44:45], v[54:55] offset:1024
	flat_store_dwordx2 v[44:45], v[50:51] offset:1536
	s_and_saveexec_b64 s[82:83], s[38:39]
	s_cbranch_execz .LBB0_473
; __device__ __forceinline__ float shx(float v, int m, int lane) { return __builtin_bit_cast(float, __builtin_amdgcn_ds_bpermute((lane ^ m) << 2, __builtin_bit_cast(int, v))); }
; __device__ __forceinline__ unsigned pk2(float lo, float hi) { return f2bf(lo) | (f2bf(hi) << 16); }
; template <int RB> __device__ __forceinline__ void res_phase(float* xout, const bf16_t* mix, const float* ssp, const float* gain, bf16_t* XN, float* rinv, int gw, int ngw, int lane) {
;     ...
;         for (int i = 0; i < RB; ++i) { const int row = row0 + i; float p = ps[i];
;             p += shx(p, 1, lane); p += shx(p, 2, lane); p += shx(p, 4, lane); p += shx(p, 8, lane);
;             const float rm = 1.0f / sqrtf(p * (1.0f / DM) + EPS);
;             f32x4 v[4]; float s = 0.f;
; #pragma unroll
;             for (int j = 0; j < 4; ++j) { const u32x2 a = xw[i][j], m = mw[i][j];
;                 f32x4 xv; xv[0] = __builtin_bit_cast(float, a.x << 16); xv[1] = __builtin_bit_cast(float, a.x & 0xffff0000u); xv[2] = __builtin_bit_cast(float, a.y << 16); xv[3] = __builtin_bit_cast(float, a.y & 0xffff0000u);
;                 f32x4 mv; mv[0] = __builtin_bit_cast(float, m.x << 16); mv[1] = __builtin_bit_cast(float, m.x & 0xffff0000u); mv[2] = __builtin_bit_cast(float, m.y << 16); mv[3] = __builtin_bit_cast(float, m.y & 0xffff0000u);
;                 v[j] = xv + mv * rm * gv[j]; s += (v[j][0] * v[j][0] + v[j][1] * v[j][1]) + (v[j][2] * v[j][2] + v[j][3] * v[j][3]); }
;             if (xout) { f32x4* xo = (f32x4*)(xout + (size_t)row * DM) + lane;
; #pragma unroll
;                 for (int j = 0; j < 4; ++j) xo[64 * j] = v[j];
;             } else {
;                 s = wave_sum(s, lane); u32x2* xr = (u32x2*)(XN + (size_t)row * DM) + lane;
; #pragma unroll
;                 for (int j = 0; j < 4; ++j) { u32x2 w; w.x = pk2(v[j][0], v[j][1]); w.y = pk2(v[j][2], v[j][3]); xr[64 * j] = w; }
;                 if (lane == 0) rinv[row] = 1.0f / sqrtf(s * (1.0f / DM) + EPS);
	s_waitcnt lgkmcnt(0)
	v_add_f32_e32 v44, v46, v47
	v_fmamk_f32 v44, v44, 0x3a800000, v217
	v_mul_f32_e32 v45, 0x4f800000, v44
	v_cmp_gt_f32_e32 vcc, s59, v44
	s_nop 1
	v_cndmask_b32_e32 v44, v44, v45, vcc
	v_sqrt_f32_e32 v45, v44
	s_nop 0
	v_add_u32_e32 v46, -1, v45
	v_fma_f32 v48, -v46, v45, v44
	v_add_u32_e32 v47, 1, v45
	v_cmp_ge_f32_e64 s[40:41], 0, v48
	s_nop 1
	v_cndmask_b32_e64 v46, v45, v46, s[40:41]
	v_fma_f32 v45, -v47, v45, v44
	v_cmp_lt_f32_e64 s[40:41], 0, v45
	s_nop 1
	v_cndmask_b32_e64 v45, v46, v47, s[40:41]
	v_mul_f32_e32 v46, 0x37800000, v45
	v_cndmask_b32_e32 v45, v45, v46, vcc
	v_cmp_class_f32_e32 vcc, v44, v218
	s_nop 1
	v_cndmask_b32_e32 v44, v45, v44, vcc
	v_div_scale_f32 v45, s[10:11], v44, v44, 1.0
	v_rcp_f32_e32 v46, v45
	s_lshl_b64 s[10:11], s[80:81], 2
	s_add_u32 s10, s5, s10
	s_addc_u32 s11, s6, s11
	v_fma_f32 v47, -v45, v46, 1.0
	v_fmac_f32_e32 v46, v47, v46
	v_div_scale_f32 v47, vcc, 1.0, v44, 1.0
	v_mul_f32_e32 v48, v47, v46
	v_fma_f32 v49, -v45, v48, v47
	v_fmac_f32_e32 v48, v49, v46
	v_fma_f32 v45, -v45, v48, v47
	v_div_fmas_f32 v45, v45, v46, v48
	v_div_fixup_f32 v46, v45, v44, 1.0
	v_mov_b64_e32 v[44:45], s[10:11]
	flat_store_dword v[44:45], v46
.LBB0_473:
	s_or_b64 exec, exec, s[82:83]
	s_nop 0
	s_waitcnt lgkmcnt(0)
	s_nop 1
	v_add_f32_dpp v44, v105, v105 quad_perm:[1,0,3,2] row_mask:0xf bank_mask:0xf
	s_nop 0
	s_waitcnt lgkmcnt(0)
	s_nop 1
	v_add_f32_dpp v44, v44, v44 quad_perm:[2,3,0,1] row_mask:0xf bank_mask:0xf
	s_nop 0
	s_waitcnt lgkmcnt(0)
	s_nop 1
	v_add_f32_dpp v44, v44, v44 row_half_mirror row_mask:0xf bank_mask:0xf
	s_nop 0
	s_waitcnt lgkmcnt(0)
	s_nop 1
	v_add_f32_dpp v44, v44, v44 row_mirror row_mask:0xf bank_mask:0xf
	v_fmamk_f32 v44, v44, 0x3a800000, v217
	v_cmp_gt_f32_e32 vcc, s59, v44
	v_mul_f32_e32 v45, 0x4f800000, v44
	s_nop 0
	v_cndmask_b32_e32 v44, v44, v45, vcc
	v_sqrt_f32_e32 v45, v44
	s_nop 0
	v_add_u32_e32 v46, -1, v45
	v_fma_f32 v47, -v46, v45, v44
	v_cmp_ge_f32_e64 s[40:41], 0, v47
	v_add_u32_e32 v47, 1, v45
	s_nop 0
	v_cndmask_b32_e64 v46, v45, v46, s[40:41]
	v_fma_f32 v45, -v47, v45, v44
	v_cmp_lt_f32_e64 s[40:41], 0, v45
	s_nop 1
	v_cndmask_b32_e64 v45, v46, v47, s[40:41]
	v_mul_f32_e32 v46, 0x37800000, v45
	v_cndmask_b32_e32 v45, v45, v46, vcc
	v_cmp_class_f32_e32 vcc, v44, v218
	s_nop 1
	v_cndmask_b32_e32 v44, v45, v44, vcc
	v_div_scale_f32 v45, s[10:11], v44, v44, 1.0
	v_rcp_f32_e32 v46, v45
	s_nop 0
	v_fma_f32 v47, -v45, v46, 1.0
	v_fmac_f32_e32 v46, v47, v46
	v_div_scale_f32 v47, vcc, 1.0, v44, 1.0
	v_mul_f32_e32 v48, v47, v46
	v_fma_f32 v49, -v45, v48, v47
	v_fmac_f32_e32 v48, v49, v46
	v_fma_f32 v45, -v45, v48, v47
	v_div_fmas_f32 v45, v45, v46, v48
	v_div_fixup_f32 v44, v45, v44, 1.0
	v_lshlrev_b32_e32 v48, 16, v40
	v_and_b32_e32 v49, 0xffff0000, v40
	v_lshlrev_b32_e32 v46, 16, v42
	v_and_b32_e32 v47, 0xffff0000, v42
	v_lshlrev_b32_e32 v40, 16, v41
	v_and_b32_e32 v41, 0xffff0000, v41
	v_pk_mul_f32 v[48:49], v[44:45], v[48:49] op_sel_hi:[0,1]
	v_lshlrev_b32_e32 v42, 16, v43
	v_and_b32_e32 v43, 0xffff0000, v43
	v_pk_mul_f32 v[40:41], v[44:45], v[40:41] op_sel_hi:[0,1]
	v_pk_fma_f32 v[46:47], v[0:1], v[48:49], v[46:47]
	v_lshlrev_b32_e32 v48, 16, v36
	v_and_b32_e32 v49, 0xffff0000, v36
	v_pk_fma_f32 v[40:41], v[2:3], v[40:41], v[42:43]
	v_lshlrev_b32_e32 v42, 16, v38
	v_and_b32_e32 v43, 0xffff0000, v38
	v_lshlrev_b32_e32 v36, 16, v37
	v_and_b32_e32 v37, 0xffff0000, v37
	v_pk_mul_f32 v[48:49], v[44:45], v[48:49] op_sel_hi:[0,1]
	v_lshlrev_b32_e32 v38, 16, v39
	v_and_b32_e32 v39, 0xffff0000, v39
	v_pk_mul_f32 v[36:37], v[44:45], v[36:37] op_sel_hi:[0,1]
	v_pk_fma_f32 v[42:43], v[4:5], v[48:49], v[42:43]
	v_lshlrev_b32_e32 v48, 16, v32
	v_and_b32_e32 v49, 0xffff0000, v32
	v_pk_fma_f32 v[36:37], v[6:7], v[36:37], v[38:39]
	v_lshlrev_b32_e32 v38, 16, v34
	v_and_b32_e32 v39, 0xffff0000, v34
	v_lshlrev_b32_e32 v32, 16, v33
	v_and_b32_e32 v33, 0xffff0000, v33
	v_pk_mul_f32 v[48:49], v[44:45], v[48:49] op_sel_hi:[0,1]
	v_lshlrev_b32_e32 v34, 16, v35
	v_and_b32_e32 v35, 0xffff0000, v35
	v_pk_mul_f32 v[32:33], v[44:45], v[32:33] op_sel_hi:[0,1]
	v_pk_fma_f32 v[38:39], v[8:9], v[48:49], v[38:39]
	v_lshlrev_b32_e32 v48, 16, v28
	v_and_b32_e32 v49, 0xffff0000, v28
	v_lshlrev_b32_e32 v28, 16, v29
	v_and_b32_e32 v29, 0xffff0000, v29
	v_pk_fma_f32 v[32:33], v[10:11], v[32:33], v[34:35]
	v_lshlrev_b32_e32 v34, 16, v30
	v_and_b32_e32 v35, 0xffff0000, v30
	v_lshlrev_b32_e32 v30, 16, v31
	v_and_b32_e32 v31, 0xffff0000, v31
	v_pk_mul_f32 v[28:29], v[44:45], v[28:29] op_sel_hi:[0,1]
	v_pk_fma_f32 v[30:31], v[14:15], v[28:29], v[30:31]
	v_mul_f32_e32 v28, v47, v47
	v_mul_f32_e32 v29, v41, v41
	v_pk_mul_f32 v[44:45], v[44:45], v[48:49] op_sel_hi:[0,1]
	v_fmac_f32_e32 v28, v46, v46
	v_fmac_f32_e32 v29, v40, v40
	v_pk_fma_f32 v[34:35], v[12:13], v[44:45], v[34:35]
	v_add_f32_e32 v28, v28, v29
	v_mul_f32_e32 v29, v43, v43
	v_mul_f32_e32 v44, v37, v37
	v_fmac_f32_e32 v29, v42, v42
	v_fmac_f32_e32 v44, v36, v36
	v_add_f32_e32 v29, v29, v44
	v_add_f32_e32 v28, v28, v29
	v_mul_f32_e32 v29, v39, v39
	v_mul_f32_e32 v44, v33, v33
	v_fmac_f32_e32 v29, v38, v38
	v_fmac_f32_e32 v44, v32, v32
	v_add_f32_e32 v29, v29, v44
	v_add_f32_e32 v28, v29, v28
	v_mul_f32_e32 v29, v35, v35
	v_mul_f32_e32 v44, v31, v31
	v_fmac_f32_e32 v29, v34, v34
	v_fmac_f32_e32 v44, v30, v30
	v_add_f32_e32 v29, v29, v44
	v_add_f32_e32 v28, v29, v28
	s_nop 0
	v_and_b32_sdwa v44, v40, v216 dst_sel:DWORD dst_unused:UNUSED_PAD src0_sel:WORD_1 src1_sel:DWORD
	v_and_b32_sdwa v45, v46, v216 dst_sel:DWORD dst_unused:UNUSED_PAD src0_sel:WORD_1 src1_sel:DWORD
	v_add3_u32 v45, v46, v45, s37
	v_add3_u32 v40, v40, v44, s37
	s_waitcnt lgkmcnt(0)
; __device__ __forceinline__ unsigned pk2(float lo, float hi) { return f2bf(lo) | (f2bf(hi) << 16); }
; template <int RB> __device__ __forceinline__ void res_phase(float* xout, const bf16_t* mix, const float* ssp, const float* gain, bf16_t* XN, float* rinv, int gw, int ngw, int lane) {
;     ...
;                 v[j] = xv + mv * rm * gv[j]; s += (v[j][0] * v[j][0] + v[j][1] * v[j][1]) + (v[j][2] * v[j][2] + v[j][3] * v[j][3]); }
;             if (xout) { f32x4* xo = (f32x4*)(xout + (size_t)row * DM) + lane;
; #pragma unroll
;                 for (int j = 0; j < 4; ++j) xo[64 * j] = v[j];
;             } else {
;                 s = wave_sum(s, lane); u32x2* xr = (u32x2*)(XN + (size_t)row * DM) + lane;
; #pragma unroll
;                 for (int j = 0; j < 4; ++j) { u32x2 w; w.x = pk2(v[j][0], v[j][1]); w.y = pk2(v[j][2], v[j][3]); xr[64 * j] = w; }
;                 if (lane == 0) rinv[row] = 1.0f / sqrtf(s * (1.0f / DM) + EPS);
	s_nop 1
	v_add_f32_dpp v28, v28, v28 quad_perm:[1,0,3,2] row_mask:0xf bank_mask:0xf
	s_nop 0
	v_and_b32_sdwa v44, v41, v216 dst_sel:DWORD dst_unused:UNUSED_PAD src0_sel:WORD_1 src1_sel:DWORD
	v_and_b32_sdwa v46, v47, v216 dst_sel:DWORD dst_unused:UNUSED_PAD src0_sel:WORD_1 src1_sel:DWORD
	v_add3_u32 v41, v41, v44, s37
	v_add3_u32 v44, v47, v46, s37
	s_waitcnt lgkmcnt(0)
	s_nop 1
	v_add_f32_dpp v28, v28, v28 quad_perm:[2,3,0,1] row_mask:0xf bank_mask:0xf
	s_nop 0
	v_and_b32_e32 v41, 0xffff0000, v41
	v_and_b32_e32 v44, 0xffff0000, v44
	v_or_b32_sdwa v41, v41, v40 dst_sel:DWORD dst_unused:UNUSED_PAD src0_sel:DWORD src1_sel:WORD_1
	v_or_b32_sdwa v40, v44, v45 dst_sel:DWORD dst_unused:UNUSED_PAD src0_sel:DWORD src1_sel:WORD_1
	s_waitcnt lgkmcnt(0)
	s_nop 1
	v_add_f32_dpp v28, v28, v28 row_half_mirror row_mask:0xf bank_mask:0xf
	s_nop 0
	flat_store_dwordx2 v[26:27], v[40:41]
	v_and_b32_sdwa v40, v36, v216 dst_sel:DWORD dst_unused:UNUSED_PAD src0_sel:WORD_1 src1_sel:DWORD
	v_and_b32_sdwa v41, v42, v216 dst_sel:DWORD dst_unused:UNUSED_PAD src0_sel:WORD_1 src1_sel:DWORD
	v_add3_u32 v41, v42, v41, s37
	v_add3_u32 v36, v36, v40, s37
	v_and_b32_sdwa v40, v37, v216 dst_sel:DWORD dst_unused:UNUSED_PAD src0_sel:WORD_1 src1_sel:DWORD
	v_and_b32_sdwa v42, v43, v216 dst_sel:DWORD dst_unused:UNUSED_PAD src0_sel:WORD_1 src1_sel:DWORD
	v_add3_u32 v37, v37, v40, s37
	v_add3_u32 v40, v43, v42, s37
	s_waitcnt lgkmcnt(0)
	s_nop 1
	v_add_f32_dpp v28, v28, v28 row_mirror row_mask:0xf bank_mask:0xf
	v_and_b32_e32 v37, 0xffff0000, v37
	v_and_b32_e32 v40, 0xffff0000, v40
	ds_bpermute_b32 v29, v103, v28
	v_or_b32_sdwa v37, v37, v36 dst_sel:DWORD dst_unused:UNUSED_PAD src0_sel:DWORD src1_sel:WORD_1
	v_or_b32_sdwa v36, v40, v41 dst_sel:DWORD dst_unused:UNUSED_PAD src0_sel:DWORD src1_sel:WORD_1
	flat_store_dwordx2 v[26:27], v[36:37] offset:512
	v_and_b32_sdwa v36, v32, v216 dst_sel:DWORD dst_unused:UNUSED_PAD src0_sel:WORD_1 src1_sel:DWORD
	v_and_b32_sdwa v37, v38, v216 dst_sel:DWORD dst_unused:UNUSED_PAD src0_sel:WORD_1 src1_sel:DWORD
	v_add3_u32 v37, v38, v37, s37
	v_add3_u32 v32, v32, v36, s37
	v_and_b32_sdwa v36, v33, v216 dst_sel:DWORD dst_unused:UNUSED_PAD src0_sel:WORD_1 src1_sel:DWORD
	v_and_b32_sdwa v38, v39, v216 dst_sel:DWORD dst_unused:UNUSED_PAD src0_sel:WORD_1 src1_sel:DWORD
	v_add3_u32 v33, v33, v36, s37
	v_add3_u32 v36, v39, v38, s37
	v_and_b32_e32 v33, 0xffff0000, v33
	v_and_b32_e32 v36, 0xffff0000, v36
	s_waitcnt lgkmcnt(0)
	v_add_f32_e32 v28, v28, v29
	v_or_b32_sdwa v33, v33, v32 dst_sel:DWORD dst_unused:UNUSED_PAD src0_sel:DWORD src1_sel:WORD_1
	v_or_b32_sdwa v32, v36, v37 dst_sel:DWORD dst_unused:UNUSED_PAD src0_sel:DWORD src1_sel:WORD_1
	ds_bpermute_b32 v29, v104, v28
	flat_store_dwordx2 v[26:27], v[32:33] offset:1024
	v_and_b32_sdwa v32, v30, v216 dst_sel:DWORD dst_unused:UNUSED_PAD src0_sel:WORD_1 src1_sel:DWORD
	v_and_b32_sdwa v33, v34, v216 dst_sel:DWORD dst_unused:UNUSED_PAD src0_sel:WORD_1 src1_sel:DWORD
	v_add3_u32 v33, v34, v33, s37
	v_add3_u32 v30, v30, v32, s37
	v_and_b32_sdwa v32, v31, v216 dst_sel:DWORD dst_unused:UNUSED_PAD src0_sel:WORD_1 src1_sel:DWORD
	v_and_b32_sdwa v34, v35, v216 dst_sel:DWORD dst_unused:UNUSED_PAD src0_sel:WORD_1 src1_sel:DWORD
	v_add3_u32 v31, v31, v32, s37
	v_add3_u32 v32, v35, v34, s37
	v_and_b32_e32 v31, 0xffff0000, v31
	v_and_b32_e32 v32, 0xffff0000, v32
	v_or_b32_sdwa v31, v31, v30 dst_sel:DWORD dst_unused:UNUSED_PAD src0_sel:DWORD src1_sel:WORD_1
	v_or_b32_sdwa v30, v32, v33 dst_sel:DWORD dst_unused:UNUSED_PAD src0_sel:DWORD src1_sel:WORD_1
	flat_store_dwordx2 v[26:27], v[30:31] offset:1536
	s_and_saveexec_b64 s[80:81], s[38:39]
	s_cbranch_execz .LBB0_466
	s_waitcnt lgkmcnt(0)
	v_add_f32_e32 v26, v28, v29
	v_fmamk_f32 v26, v26, 0x3a800000, v217
	v_mul_f32_e32 v27, 0x4f800000, v26
	v_cmp_gt_f32_e32 vcc, s59, v26
	s_nop 1
	v_cndmask_b32_e32 v26, v26, v27, vcc
	v_sqrt_f32_e32 v27, v26
	s_nop 0
	v_add_u32_e32 v28, -1, v27
	v_fma_f32 v30, -v28, v27, v26
	v_add_u32_e32 v29, 1, v27
	v_cmp_ge_f32_e64 s[40:41], 0, v30
	s_nop 1
	v_cndmask_b32_e64 v28, v27, v28, s[40:41]
	v_fma_f32 v27, -v29, v27, v26
	v_cmp_lt_f32_e64 s[40:41], 0, v27
	s_nop 1
	v_cndmask_b32_e64 v27, v28, v29, s[40:41]
	v_mul_f32_e32 v28, 0x37800000, v27
	v_cndmask_b32_e32 v27, v27, v28, vcc
	v_cmp_class_f32_e32 vcc, v26, v218
	s_nop 1
	v_cndmask_b32_e32 v26, v27, v26, vcc
	v_div_scale_f32 v27, s[10:11], v26, v26, 1.0
	v_rcp_f32_e32 v28, v27
	s_lshl_b64 s[10:11], s[78:79], 2
	s_add_u32 s10, s5, s10
	s_addc_u32 s11, s6, s11
	v_fma_f32 v29, -v27, v28, 1.0
	v_fmac_f32_e32 v28, v29, v28
	v_div_scale_f32 v29, vcc, 1.0, v26, 1.0
	v_mul_f32_e32 v30, v29, v28
	v_fma_f32 v31, -v27, v30, v29
	v_fmac_f32_e32 v30, v31, v28
	v_fma_f32 v27, -v27, v30, v29
	v_div_fmas_f32 v27, v27, v28, v30
	v_div_fixup_f32 v28, v27, v26, 1.0
	v_mov_b64_e32 v[26:27], s[10:11]
	flat_store_dword v[26:27], v28
	s_branch .LBB0_466

; __device__ __forceinline__ float shx(float v, int m, int lane) { return __builtin_bit_cast(float, __builtin_amdgcn_ds_bpermute((lane ^ m) << 2, __builtin_bit_cast(int, v))); }
; template <int RB> __device__ __forceinline__ void res_phase(float* xout, const bf16_t* mix, const float* ssp, const float* gain, bf16_t* XN, float* rinv, int gw, int ngw, int lane) {
;     ...
;     for (int row0 = rbase; row0 < rend; row0 += rstep) {
;         float ps[RB]; u32x2 xw[RB][4], mw[RB][4];
; #pragma unroll
;         for (int i = 0; i < RB; ++i) { const int row = row0 + i; ps[i] = ssp[(size_t)row * 16 + (lane & 15)];
;             const u32x2* xr = (const u32x2*)(XN + (size_t)row * DM) + lane; const u32x2* mr = (const u32x2*)(mix + (size_t)row * DM) + lane;
; #pragma unroll
;             for (int j = 0; j < 4; ++j) { xw[i][j] = xr[64 * j]; mw[i][j] = mr[64 * j]; } }
; #pragma unroll
;         for (int i = 0; i < RB; ++i) { const int row = row0 + i; float p = ps[i];
;             p += shx(p, 1, lane); p += shx(p, 2, lane); p += shx(p, 4, lane); p += shx(p, 8, lane);
;             const float rm = 1.0f / sqrtf(p * (1.0f / DM) + EPS);
;             f32x4 v[4]; float s = 0.f;
; #pragma unroll
;             for (int j = 0; j < 4; ++j) { const u32x2 a = xw[i][j], m = mw[i][j];
;                 f32x4 xv; xv[0] = __builtin_bit_cast(float, a.x << 16); xv[1] = __builtin_bit_cast(float, a.x & 0xffff0000u); xv[2] = __builtin_bit_cast(float, a.y << 16); xv[3] = __builtin_bit_cast(float, a.y & 0xffff0000u);
;                 f32x4 mv; mv[0] = __builtin_bit_cast(float, m.x << 16); mv[1] = __builtin_bit_cast(float, m.x & 0xffff0000u); mv[2] = __builtin_bit_cast(float, m.y << 16); mv[3] = __builtin_bit_cast(float, m.y & 0xffff0000u);
;                 v[j] = xv + mv * rm * gv[j]; s += (v[j][0] * v[j][0] + v[j][1] * v[j][1]) + (v[j][2] * v[j][2] + v[j][3] * v[j][3]); }
;             if (xout) { f32x4* xo = (f32x4*)(xout + (size_t)row * DM) + lane;
; #pragma unroll
;                 for (int j = 0; j < 4; ++j) xo[64 * j] = v[j];
.LBB0_719:
	v_lshl_add_u64 v[16:17], s[0:1], 0, v[44:45]
	v_add_co_u32_e32 v46, vcc, 0x400000, v16
	v_lshl_add_u64 v[82:83], s[0:1], 0, v[40:41]
	s_nop 0
	v_addc_co_u32_e32 v47, vcc, 0, v17, vcc
	flat_load_dword v100, v[46:47]
	s_waitcnt lgkmcnt(0)
	v_add_co_u32_e32 v48, vcc, 0x3800000, v82
	s_add_i32 s84, s2, 2
	s_nop 0
	v_addc_co_u32_e32 v49, vcc, 0, v83, vcc
	v_add_co_u32_e32 v50, vcc, 0x7800000, v82
	s_ashr_i32 s85, s84, 31
	s_nop 0
	v_addc_co_u32_e32 v51, vcc, 0, v83, vcc
	s_lshl_b64 s[10:11], s[84:85], 6
	s_add_i32 s82, s2, 3
	flat_load_dwordx2 v[16:17], v[48:49]
	flat_load_dwordx2 v[18:19], v[50:51]
	flat_load_dwordx2 v[22:23], v[48:49] offset:512
	flat_load_dwordx2 v[20:21], v[50:51] offset:512
	flat_load_dwordx2 v[26:27], v[48:49] offset:1024
	flat_load_dwordx2 v[24:25], v[50:51] offset:1024
	flat_load_dwordx2 v[30:31], v[48:49] offset:1536
	flat_load_dwordx2 v[28:29], v[50:51] offset:1536
	flat_load_dword v109, v[46:47] offset:64
	flat_load_dwordx2 v[98:99], v[48:49] offset:2048
	flat_load_dwordx2 v[96:97], v[50:51] offset:2048
	flat_load_dwordx2 v[94:95], v[48:49] offset:2560
	flat_load_dwordx2 v[92:93], v[50:51] offset:2560
	flat_load_dwordx2 v[90:91], v[48:49] offset:3072
	flat_load_dwordx2 v[88:89], v[50:51] offset:3072
	flat_load_dwordx2 v[86:87], v[48:49] offset:3584
	flat_load_dwordx2 v[84:85], v[50:51] offset:3584
	v_lshl_add_u64 v[46:47], v[32:33], 0, s[10:11]
	s_lshl_b64 s[10:11], s[84:85], 11
	s_ashr_i32 s83, s82, 31
	flat_load_dword v108, v[46:47]
	v_lshl_add_u64 v[64:65], v[34:35], 0, s[10:11]
	v_lshl_add_u64 v[46:47], v[36:37], 0, s[10:11]
	s_lshl_b64 s[10:11], s[82:83], 6
	flat_load_dwordx2 v[80:81], v[64:65]
	flat_load_dwordx2 v[78:79], v[46:47]
	flat_load_dwordx2 v[76:77], v[64:65] offset:512
	flat_load_dwordx2 v[74:75], v[46:47] offset:512
	flat_load_dwordx2 v[72:73], v[64:65] offset:1024
	flat_load_dwordx2 v[70:71], v[46:47] offset:1024
	flat_load_dwordx2 v[68:69], v[64:65] offset:1536
	flat_load_dwordx2 v[66:67], v[46:47] offset:1536
	v_lshl_add_u64 v[46:47], v[32:33], 0, s[10:11]
	s_lshl_b64 s[10:11], s[82:83], 11
	flat_load_dword v107, v[46:47]
	v_lshl_add_u64 v[46:47], v[34:35], 0, s[10:11]
	v_lshl_add_u64 v[50:51], v[36:37], 0, s[10:11]
	flat_load_dwordx2 v[62:63], v[46:47]
	flat_load_dwordx2 v[60:61], v[50:51]
	flat_load_dwordx2 v[58:59], v[46:47] offset:512
	flat_load_dwordx2 v[56:57], v[50:51] offset:512
	flat_load_dwordx2 v[54:55], v[46:47] offset:1024
	flat_load_dwordx2 v[52:53], v[50:51] offset:1024
	flat_load_dwordx2 v[48:49], v[46:47] offset:1536
	s_nop 0
	flat_load_dwordx2 v[50:51], v[50:51] offset:1536
	s_waitcnt vmcnt(0) lgkmcnt(0)
	s_nop 0
	s_waitcnt lgkmcnt(0)
	s_nop 1
	v_add_f32_dpp v100, v100, v100 quad_perm:[1,0,3,2] row_mask:0xf bank_mask:0xf
	s_nop 0
	s_waitcnt lgkmcnt(0)
	s_nop 1
	v_add_f32_dpp v100, v100, v100 quad_perm:[2,3,0,1] row_mask:0xf bank_mask:0xf
	s_nop 0
	s_waitcnt lgkmcnt(0)
	s_nop 1
	v_add_f32_dpp v100, v100, v100 row_half_mirror row_mask:0xf bank_mask:0xf
	s_nop 0
	s_waitcnt lgkmcnt(0)
	s_nop 1
	v_add_f32_dpp v100, v100, v100 row_mirror row_mask:0xf bank_mask:0xf
	v_fmamk_f32 v100, v100, 0x3a800000, v217
	v_cmp_gt_f32_e32 vcc, s59, v100
	v_mul_f32_e32 v110, 0x4f800000, v100
	s_nop 0
	v_cndmask_b32_e32 v100, v100, v110, vcc
	v_sqrt_f32_e32 v110, v100
	s_nop 0
	v_add_u32_e32 v111, -1, v110
	v_fma_f32 v112, -v111, v110, v100
	v_cmp_ge_f32_e64 s[40:41], 0, v112
	v_add_u32_e32 v112, 1, v110
	s_nop 0
	v_cndmask_b32_e64 v111, v110, v111, s[40:41]
	v_fma_f32 v110, -v112, v110, v100
	v_cmp_lt_f32_e64 s[40:41], 0, v110
	s_nop 1
	v_cndmask_b32_e64 v110, v111, v112, s[40:41]
	v_mul_f32_e32 v111, 0x37800000, v110
	v_cndmask_b32_e32 v110, v110, v111, vcc
	v_cmp_class_f32_e32 vcc, v100, v218
	s_nop 1
	v_cndmask_b32_e32 v100, v110, v100, vcc
	v_div_scale_f32 v110, s[10:11], v100, v100, 1.0
	v_rcp_f32_e32 v111, v110
	s_nop 0
	v_fma_f32 v112, -v110, v111, 1.0
	v_fmac_f32_e32 v111, v112, v111
	v_div_scale_f32 v112, vcc, 1.0, v100, 1.0
	v_mul_f32_e32 v113, v112, v111
	v_fma_f32 v114, -v110, v113, v112
	v_fmac_f32_e32 v113, v114, v111
	v_fma_f32 v110, -v110, v113, v112
	v_div_fmas_f32 v110, v110, v111, v113
	v_div_fixup_f32 v100, v110, v100, 1.0
	v_lshlrev_b32_e32 v112, 16, v18
	v_and_b32_e32 v113, 0xffff0000, v18
	v_lshlrev_b32_e32 v18, 16, v19
	v_and_b32_e32 v19, 0xffff0000, v19
	v_lshlrev_b32_e32 v110, 16, v16
	v_and_b32_e32 v111, 0xffff0000, v16
	v_lshlrev_b32_e32 v16, 16, v17
	v_and_b32_e32 v17, 0xffff0000, v17
	v_pk_mul_f32 v[112:113], v[100:101], v[112:113] op_sel_hi:[0,1]
	v_pk_mul_f32 v[18:19], v[100:101], v[18:19] op_sel_hi:[0,1]
	v_pk_fma_f32 v[18:19], v[2:3], v[18:19], v[16:17]
	v_pk_fma_f32 v[16:17], v[0:1], v[112:113], v[110:111]
	v_lshlrev_b32_e32 v112, 16, v20
	v_and_b32_e32 v113, 0xffff0000, v20
	v_lshlrev_b32_e32 v20, 16, v21
	v_and_b32_e32 v21, 0xffff0000, v21
	v_lshlrev_b32_e32 v110, 16, v22
	v_and_b32_e32 v111, 0xffff0000, v22
	v_lshlrev_b32_e32 v22, 16, v23
	v_and_b32_e32 v23, 0xffff0000, v23
	v_pk_mul_f32 v[112:113], v[100:101], v[112:113] op_sel_hi:[0,1]
	v_pk_mul_f32 v[20:21], v[100:101], v[20:21] op_sel_hi:[0,1]
	v_pk_fma_f32 v[22:23], v[6:7], v[20:21], v[22:23]
	v_pk_fma_f32 v[20:21], v[4:5], v[112:113], v[110:111]
	v_lshlrev_b32_e32 v112, 16, v24
	v_and_b32_e32 v113, 0xffff0000, v24
	v_lshlrev_b32_e32 v24, 16, v25
	v_and_b32_e32 v25, 0xffff0000, v25
	v_lshlrev_b32_e32 v110, 16, v26
	v_and_b32_e32 v111, 0xffff0000, v26
	v_lshlrev_b32_e32 v26, 16, v27
	v_and_b32_e32 v27, 0xffff0000, v27
	v_pk_mul_f32 v[112:113], v[100:101], v[112:113] op_sel_hi:[0,1]
	v_pk_mul_f32 v[24:25], v[100:101], v[24:25] op_sel_hi:[0,1]
	v_pk_fma_f32 v[26:27], v[10:11], v[24:25], v[26:27]
	v_pk_fma_f32 v[24:25], v[8:9], v[112:113], v[110:111]
	v_lshlrev_b32_e32 v112, 16, v28
	v_and_b32_e32 v113, 0xffff0000, v28
	v_lshlrev_b32_e32 v28, 16, v29
	v_and_b32_e32 v29, 0xffff0000, v29
	v_lshlrev_b32_e32 v110, 16, v30
	v_and_b32_e32 v111, 0xffff0000, v30
	v_lshlrev_b32_e32 v30, 16, v31
	v_and_b32_e32 v31, 0xffff0000, v31
	v_pk_mul_f32 v[112:113], v[100:101], v[112:113] op_sel_hi:[0,1]
	v_pk_mul_f32 v[28:29], v[100:101], v[28:29] op_sel_hi:[0,1]
	v_cndmask_b32_e64 v100, 0, 1, s[70:71]
	v_pk_fma_f32 v[30:31], v[14:15], v[28:29], v[30:31]
	v_pk_fma_f32 v[28:29], v[12:13], v[112:113], v[110:111]
	v_cmp_ne_u32_e64 s[40:41], 1, v100
	s_andn2_b64 vcc, exec, s[70:71]
	s_cbranch_vccnz .LBB0_721
	global_store_dwordx4 v[42:43], v[16:19], off offset:-4096
	global_store_dwordx4 v[42:43], v[20:23], off offset:-3072
	global_store_dwordx4 v[42:43], v[24:27], off offset:-2048
	global_store_dwordx4 v[42:43], v[28:31], off offset:-1024
	s_cbranch_execz .LBB0_722
	s_branch .LBB0_725
; __device__ __forceinline__ unsigned pk2(float lo, float hi) { return f2bf(lo) | (f2bf(hi) << 16); }
; template <int RB> __device__ __forceinline__ void res_phase(float* xout, const bf16_t* mix, const float* ssp, const float* gain, bf16_t* XN, float* rinv, int gw, int ngw, int lane) {
;     ...
;                 v[j] = xv + mv * rm * gv[j]; s += (v[j][0] * v[j][0] + v[j][1] * v[j][1]) + (v[j][2] * v[j][2] + v[j][3] * v[j][3]); }
;             if (xout) { f32x4* xo = (f32x4*)(xout + (size_t)row * DM) + lane;
; #pragma unroll
;                 for (int j = 0; j < 4; ++j) xo[64 * j] = v[j];
;             } else {
;                 s = wave_sum(s, lane); u32x2* xr = (u32x2*)(XN + (size_t)row * DM) + lane;
; #pragma unroll
;                 for (int j = 0; j < 4; ++j) { u32x2 w; w.x = pk2(v[j][0], v[j][1]); w.y = pk2(v[j][2], v[j][3]); xr[64 * j] = w; }
;                 if (lane == 0) rinv[row] = 1.0f / sqrtf(s * (1.0f / DM) + EPS);
;             } }
.LBB0_721:
.LBB0_722:
	v_mul_f32_e32 v100, v17, v17
	v_mul_f32_e32 v110, v19, v19
	v_fmac_f32_e32 v100, v16, v16
	v_fmac_f32_e32 v110, v18, v18
	v_add_f32_e32 v100, v100, v110
	v_mul_f32_e32 v110, v21, v21
	v_mul_f32_e32 v111, v23, v23
	v_fmac_f32_e32 v110, v20, v20
	v_fmac_f32_e32 v111, v22, v22
	v_add_f32_e32 v110, v110, v111
	v_add_f32_e32 v100, v100, v110
	v_mul_f32_e32 v110, v25, v25
	v_mul_f32_e32 v111, v27, v27
	v_fmac_f32_e32 v110, v24, v24
	v_fmac_f32_e32 v111, v26, v26
	v_add_f32_e32 v110, v110, v111
	v_add_f32_e32 v100, v110, v100
	v_mul_f32_e32 v110, v29, v29
	v_mul_f32_e32 v111, v31, v31
	v_fmac_f32_e32 v110, v28, v28
	v_fmac_f32_e32 v111, v30, v30
	v_add_f32_e32 v110, v110, v111
	v_add_f32_e32 v100, v110, v100
	s_nop 0
	v_bfe_u32 v111, v16, 16, 1
	v_add3_u32 v16, v16, v111, s37
	v_bfe_u32 v111, v17, 16, 1
	v_lshrrev_b32_e32 v16, 16, v16
	s_waitcnt lgkmcnt(0)
	s_nop 1
	v_add_f32_dpp v100, v100, v100 quad_perm:[1,0,3,2] row_mask:0xf bank_mask:0xf
	s_nop 0
	v_add3_u32 v17, v17, v111, s37
	v_and_or_b32 v16, v17, s57, v16
	v_bfe_u32 v17, v18, 16, 1
	v_add3_u32 v17, v18, v17, s37
	s_waitcnt lgkmcnt(0)
	s_nop 1
	v_add_f32_dpp v100, v100, v100 quad_perm:[2,3,0,1] row_mask:0xf bank_mask:0xf
	v_bfe_u32 v18, v19, 16, 1
	s_nop 0
	s_mov_b64 s[10:11], 0x3800000
	v_lshrrev_b32_e32 v17, 16, v17
	v_add3_u32 v18, v19, v18, s37
	v_lshl_add_u64 v[112:113], v[82:83], 0, s[10:11]
	v_and_or_b32 v17, v18, s57, v17
	flat_store_dwordx2 v[112:113], v[16:17]
	v_bfe_u32 v16, v20, 16, 1
	v_add3_u32 v16, v20, v16, s37
	v_bfe_u32 v17, v21, 16, 1
	v_lshrrev_b32_e32 v16, 16, v16
	v_add3_u32 v17, v21, v17, s37
	s_waitcnt lgkmcnt(0)
	s_nop 1
	v_add_f32_dpp v100, v100, v100 row_half_mirror row_mask:0xf bank_mask:0xf
	v_and_or_b32 v16, v17, s57, v16
	v_bfe_u32 v17, v22, 16, 1
	s_nop 0
	v_add3_u32 v17, v22, v17, s37
	v_bfe_u32 v18, v23, 16, 1
	s_mov_b64 s[10:11], 0x3800200
	v_lshrrev_b32_e32 v17, 16, v17
	v_add3_u32 v18, v23, v18, s37
	v_lshl_add_u64 v[114:115], v[82:83], 0, s[10:11]
	v_and_or_b32 v17, v18, s57, v17
	flat_store_dwordx2 v[114:115], v[16:17]
	v_bfe_u32 v16, v24, 16, 1
	v_add3_u32 v16, v24, v16, s37
	v_bfe_u32 v17, v25, 16, 1
	s_waitcnt lgkmcnt(0)
	s_nop 1
	v_add_f32_dpp v100, v100, v100 row_mirror row_mask:0xf bank_mask:0xf
	v_lshrrev_b32_e32 v16, 16, v16
	v_add3_u32 v17, v25, v17, s37
	ds_bpermute_b32 v110, v105, v100
	v_and_or_b32 v16, v17, s57, v16
	v_bfe_u32 v17, v26, 16, 1
	v_add3_u32 v17, v26, v17, s37
	v_bfe_u32 v18, v27, 16, 1
	s_mov_b64 s[10:11], 0x3800400
	v_lshrrev_b32_e32 v17, 16, v17
	v_add3_u32 v18, v27, v18, s37
	v_lshl_add_u64 v[116:117], v[82:83], 0, s[10:11]
	v_and_or_b32 v17, v18, s57, v17
	flat_store_dwordx2 v[116:117], v[16:17]
	v_bfe_u32 v16, v28, 16, 1
	s_waitcnt lgkmcnt(0)
	v_add_f32_e32 v100, v100, v110
	v_add3_u32 v16, v28, v16, s37
	v_bfe_u32 v17, v29, 16, 1
	ds_bpermute_b32 v110, v106, v100
	v_lshrrev_b32_e32 v16, 16, v16
	v_add3_u32 v17, v29, v17, s37
	v_and_or_b32 v16, v17, s57, v16
	v_bfe_u32 v17, v30, 16, 1
	v_add3_u32 v17, v30, v17, s37
	v_bfe_u32 v18, v31, 16, 1
	s_mov_b64 s[10:11], 0x3800600
	v_lshrrev_b32_e32 v17, 16, v17
	v_add3_u32 v18, v31, v18, s37
	v_lshl_add_u64 v[118:119], v[82:83], 0, s[10:11]
	v_and_or_b32 v17, v18, s57, v17
	flat_store_dwordx2 v[118:119], v[16:17]
	s_and_saveexec_b64 s[86:87], s[38:39]
	s_cbranch_execz .LBB0_724
	s_waitcnt lgkmcnt(0)
	v_add_f32_e32 v16, v100, v110
	v_fmamk_f32 v16, v16, 0x3a800000, v217
	v_mul_f32_e32 v17, 0x4f800000, v16
	v_cmp_gt_f32_e32 vcc, s59, v16
	s_add_u32 s3, s0, s72
	s_addc_u32 s7, s1, s73
	v_cndmask_b32_e32 v16, v16, v17, vcc
	v_sqrt_f32_e32 v17, v16
	s_nop 0
	v_add_u32_e32 v18, -1, v17
	v_fma_f32 v20, -v18, v17, v16
	v_add_u32_e32 v19, 1, v17
	v_cmp_ge_f32_e64 s[42:43], 0, v20
	s_nop 1
	v_cndmask_b32_e64 v18, v17, v18, s[42:43]
	v_fma_f32 v17, -v19, v17, v16
	v_cmp_lt_f32_e64 s[42:43], 0, v17
	s_nop 1
	v_cndmask_b32_e64 v17, v18, v19, s[42:43]
	v_mul_f32_e32 v18, 0x37800000, v17
	v_cndmask_b32_e32 v17, v17, v18, vcc
	v_cmp_class_f32_e32 vcc, v16, v218
	s_nop 1
	v_cndmask_b32_e32 v16, v17, v16, vcc
	v_div_scale_f32 v17, s[10:11], v16, v16, 1.0
	v_rcp_f32_e32 v18, v17
	s_nop 0
	v_fma_f32 v19, -v17, v18, 1.0
	v_fmac_f32_e32 v18, v19, v18
	v_div_scale_f32 v19, vcc, 1.0, v16, 1.0
	v_mul_f32_e32 v20, v19, v18
	v_fma_f32 v21, -v17, v20, v19
	v_fmac_f32_e32 v20, v21, v18
	v_fma_f32 v17, -v17, v20, v19
	v_div_fmas_f32 v17, v17, v18, v20
	v_div_fixup_f32 v18, v17, v16, 1.0
	v_mov_b32_e32 v16, s3
	v_add_co_u32_e32 v16, vcc, 0x300000, v16
	v_mov_b32_e32 v17, s7
	s_nop 0
	v_addc_co_u32_e32 v17, vcc, 0, v17, vcc
	flat_store_dword v[16:17], v18

; __device__ __forceinline__ float shx(float v, int m, int lane) { return __builtin_bit_cast(float, __builtin_amdgcn_ds_bpermute((lane ^ m) << 2, __builtin_bit_cast(int, v))); }
; template <int RB> __device__ __forceinline__ void res_phase(float* xout, const bf16_t* mix, const float* ssp, const float* gain, bf16_t* XN, float* rinv, int gw, int ngw, int lane) {
;     ...
;         for (int i = 0; i < RB; ++i) { const int row = row0 + i; float p = ps[i];
;             p += shx(p, 1, lane); p += shx(p, 2, lane); p += shx(p, 4, lane); p += shx(p, 8, lane);
;             const float rm = 1.0f / sqrtf(p * (1.0f / DM) + EPS);
;             f32x4 v[4]; float s = 0.f;
; #pragma unroll
;             for (int j = 0; j < 4; ++j) { const u32x2 a = xw[i][j], m = mw[i][j];
;                 f32x4 xv; xv[0] = __builtin_bit_cast(float, a.x << 16); xv[1] = __builtin_bit_cast(float, a.x & 0xffff0000u); xv[2] = __builtin_bit_cast(float, a.y << 16); xv[3] = __builtin_bit_cast(float, a.y & 0xffff0000u);
;                 f32x4 mv; mv[0] = __builtin_bit_cast(float, m.x << 16); mv[1] = __builtin_bit_cast(float, m.x & 0xffff0000u); mv[2] = __builtin_bit_cast(float, m.y << 16); mv[3] = __builtin_bit_cast(float, m.y & 0xffff0000u);
;                 v[j] = xv + mv * rm * gv[j]; s += (v[j][0] * v[j][0] + v[j][1] * v[j][1]) + (v[j][2] * v[j][2] + v[j][3] * v[j][3]); }
;             if (xout) { f32x4* xo = (f32x4*)(xout + (size_t)row * DM) + lane;
; #pragma unroll
;                 for (int j = 0; j < 4; ++j) xo[64 * j] = v[j];
.LBB0_725:
	s_nop 0
	v_lshlrev_b32_e32 v22, 16, v97
	v_and_b32_e32 v23, 0xffff0000, v97
	v_lshlrev_b32_e32 v24, 16, v92
	v_and_b32_e32 v25, 0xffff0000, v92
	s_waitcnt lgkmcnt(0)
	s_nop 1
	v_add_f32_dpp v16, v109, v109 quad_perm:[1,0,3,2] row_mask:0xf bank_mask:0xf
	s_nop 0
	v_lshlrev_b32_e32 v26, 16, v93
	v_and_b32_e32 v27, 0xffff0000, v93
	v_lshlrev_b32_e32 v30, 16, v88
	v_and_b32_e32 v31, 0xffff0000, v88
	s_waitcnt lgkmcnt(0)
	s_nop 1
	v_add_f32_dpp v16, v16, v16 quad_perm:[2,3,0,1] row_mask:0xf bank_mask:0xf
	s_nop 0
	v_lshlrev_b32_e32 v88, 16, v89
	v_and_b32_e32 v89, 0xffff0000, v89
	s_waitcnt lgkmcnt(0)
	s_nop 1
	v_add_f32_dpp v16, v16, v16 row_half_mirror row_mask:0xf bank_mask:0xf
	s_nop 0
	s_waitcnt lgkmcnt(0)
	s_nop 1
	v_add_f32_dpp v16, v16, v16 row_mirror row_mask:0xf bank_mask:0xf
	v_fmamk_f32 v16, v16, 0x3a800000, v217
	v_cmp_gt_f32_e32 vcc, s59, v16
	v_mul_f32_e32 v17, 0x4f800000, v16
	s_nop 0
	v_cndmask_b32_e32 v16, v16, v17, vcc
	v_sqrt_f32_e32 v17, v16
	s_nop 0
	v_add_u32_e32 v18, -1, v17
	v_fma_f32 v19, -v18, v17, v16
	v_cmp_ge_f32_e64 s[42:43], 0, v19
	v_add_u32_e32 v19, 1, v17
	s_nop 0
	v_cndmask_b32_e64 v18, v17, v18, s[42:43]
	v_fma_f32 v17, -v19, v17, v16
	v_cmp_lt_f32_e64 s[42:43], 0, v17
	s_nop 1
	v_cndmask_b32_e64 v17, v18, v19, s[42:43]
	v_mul_f32_e32 v18, 0x37800000, v17
	v_cndmask_b32_e32 v17, v17, v18, vcc
	v_cmp_class_f32_e32 vcc, v16, v218
	s_nop 1
	v_cndmask_b32_e32 v16, v17, v16, vcc
	v_div_scale_f32 v17, s[10:11], v16, v16, 1.0
	v_rcp_f32_e32 v18, v17
	s_nop 0
	v_fma_f32 v19, -v17, v18, 1.0
	v_fmac_f32_e32 v18, v19, v18
	v_div_scale_f32 v19, vcc, 1.0, v16, 1.0
	v_mul_f32_e32 v20, v19, v18
	v_fma_f32 v21, -v17, v20, v19
	v_fmac_f32_e32 v20, v21, v18
	v_fma_f32 v17, -v17, v20, v19
	v_div_fmas_f32 v17, v17, v18, v20
	v_div_fixup_f32 v28, v17, v16, 1.0
	v_lshlrev_b32_e32 v20, 16, v96
	v_and_b32_e32 v21, 0xffff0000, v96
	v_lshlrev_b32_e32 v16, 16, v98
	v_and_b32_e32 v17, 0xffff0000, v98
	v_lshlrev_b32_e32 v18, 16, v99
	v_and_b32_e32 v19, 0xffff0000, v99
	v_pk_mul_f32 v[20:21], v[28:29], v[20:21] op_sel_hi:[0,1]
	v_pk_mul_f32 v[22:23], v[28:29], v[22:23] op_sel_hi:[0,1]
	v_pk_fma_f32 v[18:19], v[2:3], v[22:23], v[18:19]
	v_pk_fma_f32 v[16:17], v[0:1], v[20:21], v[16:17]
	v_lshlrev_b32_e32 v20, 16, v94
	v_and_b32_e32 v21, 0xffff0000, v94
	v_lshlrev_b32_e32 v22, 16, v95
	v_and_b32_e32 v23, 0xffff0000, v95
	v_pk_mul_f32 v[24:25], v[28:29], v[24:25] op_sel_hi:[0,1]
	v_pk_mul_f32 v[26:27], v[28:29], v[26:27] op_sel_hi:[0,1]
	v_pk_fma_f32 v[22:23], v[6:7], v[26:27], v[22:23]
	v_pk_fma_f32 v[20:21], v[4:5], v[24:25], v[20:21]
	v_lshlrev_b32_e32 v24, 16, v90
	v_and_b32_e32 v25, 0xffff0000, v90
	v_lshlrev_b32_e32 v26, 16, v91
	v_and_b32_e32 v27, 0xffff0000, v91
	v_pk_mul_f32 v[30:31], v[28:29], v[30:31] op_sel_hi:[0,1]
	v_pk_mul_f32 v[88:89], v[28:29], v[88:89] op_sel_hi:[0,1]
	v_pk_fma_f32 v[26:27], v[10:11], v[88:89], v[26:27]
	v_pk_fma_f32 v[24:25], v[8:9], v[30:31], v[24:25]
	v_lshlrev_b32_e32 v88, 16, v86
	v_and_b32_e32 v89, 0xffff0000, v86
	v_lshlrev_b32_e32 v30, 16, v87
	v_and_b32_e32 v31, 0xffff0000, v87
	v_lshlrev_b32_e32 v86, 16, v84
	v_and_b32_e32 v87, 0xffff0000, v84
	v_lshlrev_b32_e32 v84, 16, v85
	v_and_b32_e32 v85, 0xffff0000, v85
	v_pk_mul_f32 v[86:87], v[28:29], v[86:87] op_sel_hi:[0,1]
	v_pk_mul_f32 v[28:29], v[28:29], v[84:85] op_sel_hi:[0,1]
	v_pk_fma_f32 v[30:31], v[14:15], v[28:29], v[30:31]
	v_pk_fma_f32 v[28:29], v[12:13], v[86:87], v[88:89]
	s_and_b64 vcc, exec, s[40:41]
	s_cbranch_vccnz .LBB0_727
	global_store_dwordx4 v[42:43], v[16:19], off
	global_store_dwordx4 v[42:43], v[20:23], off offset:1024
	global_store_dwordx4 v[42:43], v[24:27], off offset:2048
	global_store_dwordx4 v[42:43], v[28:31], off offset:3072
	s_cbranch_execz .LBB0_728
	s_branch .LBB0_731
; __device__ __forceinline__ unsigned pk2(float lo, float hi) { return f2bf(lo) | (f2bf(hi) << 16); }
; template <int RB> __device__ __forceinline__ void res_phase(float* xout, const bf16_t* mix, const float* ssp, const float* gain, bf16_t* XN, float* rinv, int gw, int ngw, int lane) {
;     ...
;             } else {
;                 s = wave_sum(s, lane); u32x2* xr = (u32x2*)(XN + (size_t)row * DM) + lane;
; #pragma unroll
;                 for (int j = 0; j < 4; ++j) { u32x2 w; w.x = pk2(v[j][0], v[j][1]); w.y = pk2(v[j][2], v[j][3]); xr[64 * j] = w; }
;                 if (lane == 0) rinv[row] = 1.0f / sqrtf(s * (1.0f / DM) + EPS);
;             } }
.LBB0_727:
.LBB0_728:
	v_mul_f32_e32 v84, v17, v17
	v_mul_f32_e32 v85, v19, v19
	v_fmac_f32_e32 v84, v16, v16
	v_fmac_f32_e32 v85, v18, v18
	v_add_f32_e32 v84, v84, v85
	v_mul_f32_e32 v85, v21, v21
	v_mul_f32_e32 v86, v23, v23
	v_fmac_f32_e32 v85, v20, v20
	v_fmac_f32_e32 v86, v22, v22
	v_add_f32_e32 v85, v85, v86
	v_add_f32_e32 v84, v84, v85
	v_mul_f32_e32 v85, v25, v25
	v_mul_f32_e32 v86, v27, v27
	v_fmac_f32_e32 v85, v24, v24
	v_fmac_f32_e32 v86, v26, v26
	v_add_f32_e32 v85, v85, v86
	v_add_f32_e32 v84, v85, v84
	v_mul_f32_e32 v85, v29, v29
	v_mul_f32_e32 v86, v31, v31
	v_fmac_f32_e32 v85, v28, v28
	v_fmac_f32_e32 v86, v30, v30
	v_add_f32_e32 v85, v85, v86
	v_add_f32_e32 v84, v85, v84
	s_nop 0
	s_mov_b64 s[10:11], 0x3800800
	s_waitcnt lgkmcnt(0)
	s_nop 1
	v_add_f32_dpp v84, v84, v84 quad_perm:[1,0,3,2] row_mask:0xf bank_mask:0xf
	s_nop 0
	s_waitcnt lgkmcnt(0)
	s_nop 1
	v_add_f32_dpp v84, v84, v84 quad_perm:[2,3,0,1] row_mask:0xf bank_mask:0xf
	s_nop 0
	s_waitcnt lgkmcnt(0)
	s_nop 1
	v_add_f32_dpp v84, v84, v84 row_half_mirror row_mask:0xf bank_mask:0xf
	s_nop 0
	s_waitcnt lgkmcnt(0)
	s_nop 1
	v_add_f32_dpp v92, v84, v84 row_mirror row_mask:0xf bank_mask:0xf
	ds_bpermute_b32 v93, v105, v92
	v_lshl_add_u64 v[84:85], v[82:83], 0, s[10:11]
	s_mov_b64 s[10:11], 0x3800a00
	v_lshl_add_u64 v[86:87], v[82:83], 0, s[10:11]
	s_mov_b64 s[10:11], 0x3800c00
	v_lshl_add_u64 v[88:89], v[82:83], 0, s[10:11]
	s_mov_b64 s[10:11], 0x3800e00
	v_lshl_add_u64 v[90:91], v[82:83], 0, s[10:11]
	s_waitcnt lgkmcnt(0)
	v_add_f32_e32 v82, v92, v93
	v_bfe_u32 v92, v16, 16, 1
	v_add3_u32 v16, v16, v92, s37
	v_bfe_u32 v92, v17, 16, 1
	v_lshrrev_b32_e32 v16, 16, v16
	v_add3_u32 v17, v17, v92, s37
	v_and_or_b32 v16, v17, s57, v16
	v_bfe_u32 v17, v18, 16, 1
	v_add3_u32 v17, v18, v17, s37
	v_bfe_u32 v18, v19, 16, 1
	v_lshrrev_b32_e32 v17, 16, v17
	v_add3_u32 v18, v19, v18, s37
	v_and_or_b32 v17, v18, s57, v17
	flat_store_dwordx2 v[84:85], v[16:17]
	v_bfe_u32 v16, v20, 16, 1
	v_add3_u32 v16, v20, v16, s37
	v_bfe_u32 v17, v21, 16, 1
	v_lshrrev_b32_e32 v16, 16, v16
	v_add3_u32 v17, v21, v17, s37
	v_and_or_b32 v16, v17, s57, v16
	v_bfe_u32 v17, v22, 16, 1
	v_add3_u32 v17, v22, v17, s37
	v_bfe_u32 v18, v23, 16, 1
	v_lshrrev_b32_e32 v17, 16, v17
	v_add3_u32 v18, v23, v18, s37
	v_and_or_b32 v17, v18, s57, v17
	flat_store_dwordx2 v[86:87], v[16:17]
	v_bfe_u32 v16, v24, 16, 1
	v_add3_u32 v16, v24, v16, s37
	v_bfe_u32 v17, v25, 16, 1
	v_lshrrev_b32_e32 v16, 16, v16
	v_add3_u32 v17, v25, v17, s37
	v_and_or_b32 v16, v17, s57, v16
	v_bfe_u32 v17, v26, 16, 1
	v_add3_u32 v17, v26, v17, s37
	v_bfe_u32 v18, v27, 16, 1
	v_lshrrev_b32_e32 v17, 16, v17
	v_add3_u32 v18, v27, v18, s37
	v_and_or_b32 v17, v18, s57, v17
	flat_store_dwordx2 v[88:89], v[16:17]
	v_bfe_u32 v16, v28, 16, 1
	v_add3_u32 v16, v28, v16, s37
	v_bfe_u32 v17, v29, 16, 1
	ds_bpermute_b32 v83, v106, v82
	v_lshrrev_b32_e32 v16, 16, v16
	v_add3_u32 v17, v29, v17, s37
	v_and_or_b32 v16, v17, s57, v16
	v_bfe_u32 v17, v30, 16, 1
	v_add3_u32 v17, v30, v17, s37
	v_bfe_u32 v18, v31, 16, 1
	v_lshrrev_b32_e32 v17, 16, v17
	v_add3_u32 v18, v31, v18, s37
	v_and_or_b32 v17, v18, s57, v17
	flat_store_dwordx2 v[90:91], v[16:17]
	s_and_saveexec_b64 s[86:87], s[38:39]
	s_cbranch_execz .LBB0_730
	s_waitcnt lgkmcnt(0)
	v_add_f32_e32 v16, v82, v83
	v_fmamk_f32 v16, v16, 0x3a800000, v217
	v_mul_f32_e32 v17, 0x4f800000, v16
	v_cmp_gt_f32_e32 vcc, s59, v16
	s_add_u32 s3, s0, s72
	s_addc_u32 s7, s1, s73
	v_cndmask_b32_e32 v16, v16, v17, vcc
	v_sqrt_f32_e32 v17, v16
	s_nop 0
	v_add_u32_e32 v18, -1, v17
	v_fma_f32 v20, -v18, v17, v16
	v_add_u32_e32 v19, 1, v17
	v_cmp_ge_f32_e64 s[42:43], 0, v20
	s_nop 1
	v_cndmask_b32_e64 v18, v17, v18, s[42:43]
	v_fma_f32 v17, -v19, v17, v16
	v_cmp_lt_f32_e64 s[42:43], 0, v17
	s_nop 1
	v_cndmask_b32_e64 v17, v18, v19, s[42:43]
	v_mul_f32_e32 v18, 0x37800000, v17
	v_cndmask_b32_e32 v17, v17, v18, vcc
	v_cmp_class_f32_e32 vcc, v16, v218
	s_nop 1
	v_cndmask_b32_e32 v16, v17, v16, vcc
	v_div_scale_f32 v17, s[10:11], v16, v16, 1.0
	v_rcp_f32_e32 v18, v17
	s_nop 0
	v_fma_f32 v19, -v17, v18, 1.0
	v_fmac_f32_e32 v18, v19, v18
	v_div_scale_f32 v19, vcc, 1.0, v16, 1.0
	v_mul_f32_e32 v20, v19, v18
	v_fma_f32 v21, -v17, v20, v19
	v_fmac_f32_e32 v20, v21, v18
	v_fma_f32 v17, -v17, v20, v19
	v_div_fmas_f32 v17, v17, v18, v20
	v_div_fixup_f32 v18, v17, v16, 1.0
	v_mov_b32_e32 v16, s3
	v_add_co_u32_e32 v16, vcc, 0x300000, v16
	v_mov_b32_e32 v17, s7
	s_nop 0
	v_addc_co_u32_e32 v17, vcc, 0, v17, vcc
	flat_store_dword v[16:17], v18 offset:4

; __device__ __forceinline__ float shx(float v, int m, int lane) { return __builtin_bit_cast(float, __builtin_amdgcn_ds_bpermute((lane ^ m) << 2, __builtin_bit_cast(int, v))); }
; template <int RB> __device__ __forceinline__ void res_phase(float* xout, const bf16_t* mix, const float* ssp, const float* gain, bf16_t* XN, float* rinv, int gw, int ngw, int lane) {
;     ...
;         for (int i = 0; i < RB; ++i) { const int row = row0 + i; float p = ps[i];
;             p += shx(p, 1, lane); p += shx(p, 2, lane); p += shx(p, 4, lane); p += shx(p, 8, lane);
;             const float rm = 1.0f / sqrtf(p * (1.0f / DM) + EPS);
;             f32x4 v[4]; float s = 0.f;
; #pragma unroll
;             for (int j = 0; j < 4; ++j) { const u32x2 a = xw[i][j], m = mw[i][j];
;                 f32x4 xv; xv[0] = __builtin_bit_cast(float, a.x << 16); xv[1] = __builtin_bit_cast(float, a.x & 0xffff0000u); xv[2] = __builtin_bit_cast(float, a.y << 16); xv[3] = __builtin_bit_cast(float, a.y & 0xffff0000u);
;                 f32x4 mv; mv[0] = __builtin_bit_cast(float, m.x << 16); mv[1] = __builtin_bit_cast(float, m.x & 0xffff0000u); mv[2] = __builtin_bit_cast(float, m.y << 16); mv[3] = __builtin_bit_cast(float, m.y & 0xffff0000u);
;                 v[j] = xv + mv * rm * gv[j]; s += (v[j][0] * v[j][0] + v[j][1] * v[j][1]) + (v[j][2] * v[j][2] + v[j][3] * v[j][3]); }
;             if (xout) { f32x4* xo = (f32x4*)(xout + (size_t)row * DM) + lane;
; #pragma unroll
;                 for (int j = 0; j < 4; ++j) xo[64 * j] = v[j];
.LBB0_731:
	s_nop 0
	v_lshlrev_b32_e32 v22, 16, v79
	v_and_b32_e32 v23, 0xffff0000, v79
	v_lshlrev_b32_e32 v24, 16, v74
	v_and_b32_e32 v25, 0xffff0000, v74
	s_waitcnt lgkmcnt(0)
	s_nop 1
	v_add_f32_dpp v16, v108, v108 quad_perm:[1,0,3,2] row_mask:0xf bank_mask:0xf
	s_nop 0
	v_lshlrev_b32_e32 v26, 16, v75
	v_and_b32_e32 v27, 0xffff0000, v75
	v_lshlrev_b32_e32 v30, 16, v70
	v_and_b32_e32 v31, 0xffff0000, v70
	s_waitcnt lgkmcnt(0)
	s_nop 1
	v_add_f32_dpp v16, v16, v16 quad_perm:[2,3,0,1] row_mask:0xf bank_mask:0xf
	s_nop 0
	v_lshlrev_b32_e32 v70, 16, v71
	v_and_b32_e32 v71, 0xffff0000, v71
	s_waitcnt lgkmcnt(0)
	s_nop 1
	v_add_f32_dpp v16, v16, v16 row_half_mirror row_mask:0xf bank_mask:0xf
	s_nop 0
	s_waitcnt lgkmcnt(0)
	s_nop 1
	v_add_f32_dpp v16, v16, v16 row_mirror row_mask:0xf bank_mask:0xf
	v_fmamk_f32 v16, v16, 0x3a800000, v217
	v_cmp_gt_f32_e32 vcc, s59, v16
	v_mul_f32_e32 v17, 0x4f800000, v16
	s_nop 0
	v_cndmask_b32_e32 v16, v16, v17, vcc
	v_sqrt_f32_e32 v17, v16
	s_nop 0
	v_add_u32_e32 v18, -1, v17
	v_fma_f32 v19, -v18, v17, v16
	v_cmp_ge_f32_e64 s[42:43], 0, v19
	v_add_u32_e32 v19, 1, v17
	s_nop 0
	v_cndmask_b32_e64 v18, v17, v18, s[42:43]
	v_fma_f32 v17, -v19, v17, v16
	v_cmp_lt_f32_e64 s[42:43], 0, v17
	s_nop 1
	v_cndmask_b32_e64 v17, v18, v19, s[42:43]
	v_mul_f32_e32 v18, 0x37800000, v17
	v_cndmask_b32_e32 v17, v17, v18, vcc
	v_cmp_class_f32_e32 vcc, v16, v218
	s_nop 1
	v_cndmask_b32_e32 v16, v17, v16, vcc
	v_div_scale_f32 v17, s[10:11], v16, v16, 1.0
	v_rcp_f32_e32 v18, v17
	s_nop 0
	v_fma_f32 v19, -v17, v18, 1.0
	v_fmac_f32_e32 v18, v19, v18
	v_div_scale_f32 v19, vcc, 1.0, v16, 1.0
	v_mul_f32_e32 v20, v19, v18
	v_fma_f32 v21, -v17, v20, v19
	v_fmac_f32_e32 v20, v21, v18
	v_fma_f32 v17, -v17, v20, v19
	v_div_fmas_f32 v17, v17, v18, v20
	v_div_fixup_f32 v28, v17, v16, 1.0
	v_lshlrev_b32_e32 v20, 16, v78
	v_and_b32_e32 v21, 0xffff0000, v78
	v_lshlrev_b32_e32 v16, 16, v80
	v_and_b32_e32 v17, 0xffff0000, v80
	v_lshlrev_b32_e32 v18, 16, v81
	v_and_b32_e32 v19, 0xffff0000, v81
	v_pk_mul_f32 v[20:21], v[28:29], v[20:21] op_sel_hi:[0,1]
	v_pk_mul_f32 v[22:23], v[28:29], v[22:23] op_sel_hi:[0,1]
	v_pk_fma_f32 v[18:19], v[2:3], v[22:23], v[18:19]
	v_pk_fma_f32 v[16:17], v[0:1], v[20:21], v[16:17]
	v_lshlrev_b32_e32 v20, 16, v76
	v_and_b32_e32 v21, 0xffff0000, v76
	v_lshlrev_b32_e32 v22, 16, v77
	v_and_b32_e32 v23, 0xffff0000, v77
	v_pk_mul_f32 v[24:25], v[28:29], v[24:25] op_sel_hi:[0,1]
	v_pk_mul_f32 v[26:27], v[28:29], v[26:27] op_sel_hi:[0,1]
	v_pk_fma_f32 v[22:23], v[6:7], v[26:27], v[22:23]
	v_pk_fma_f32 v[20:21], v[4:5], v[24:25], v[20:21]
	v_lshlrev_b32_e32 v24, 16, v72
	v_and_b32_e32 v25, 0xffff0000, v72
	v_lshlrev_b32_e32 v26, 16, v73
	v_and_b32_e32 v27, 0xffff0000, v73
	v_pk_mul_f32 v[30:31], v[28:29], v[30:31] op_sel_hi:[0,1]
	v_pk_mul_f32 v[70:71], v[28:29], v[70:71] op_sel_hi:[0,1]
	v_pk_fma_f32 v[26:27], v[10:11], v[70:71], v[26:27]
	v_pk_fma_f32 v[24:25], v[8:9], v[30:31], v[24:25]
	v_lshlrev_b32_e32 v70, 16, v68
	v_and_b32_e32 v71, 0xffff0000, v68
	v_lshlrev_b32_e32 v30, 16, v69
	v_and_b32_e32 v31, 0xffff0000, v69
	v_lshlrev_b32_e32 v68, 16, v66
	v_and_b32_e32 v69, 0xffff0000, v66
	v_lshlrev_b32_e32 v66, 16, v67
	v_and_b32_e32 v67, 0xffff0000, v67
	v_pk_mul_f32 v[68:69], v[28:29], v[68:69] op_sel_hi:[0,1]
	v_pk_mul_f32 v[28:29], v[28:29], v[66:67] op_sel_hi:[0,1]
	v_pk_fma_f32 v[30:31], v[14:15], v[28:29], v[30:31]
	v_pk_fma_f32 v[28:29], v[12:13], v[68:69], v[70:71]
	s_and_b64 vcc, exec, s[40:41]
	s_cbranch_vccnz .LBB0_733
	s_lshl_b64 s[10:11], s[84:85], 12
	v_lshl_add_u64 v[66:67], v[38:39], 0, s[10:11]
	global_store_dwordx4 v[66:67], v[16:19], off
	global_store_dwordx4 v[66:67], v[20:23], off offset:1024
	global_store_dwordx4 v[66:67], v[24:27], off offset:2048
	global_store_dwordx4 v[66:67], v[28:31], off offset:3072
	s_cbranch_execz .LBB0_734
	s_branch .LBB0_737
; __device__ __forceinline__ unsigned pk2(float lo, float hi) { return f2bf(lo) | (f2bf(hi) << 16); }
; template <int RB> __device__ __forceinline__ void res_phase(float* xout, const bf16_t* mix, const float* ssp, const float* gain, bf16_t* XN, float* rinv, int gw, int ngw, int lane) {
;     ...
;             } else {
;                 s = wave_sum(s, lane); u32x2* xr = (u32x2*)(XN + (size_t)row * DM) + lane;
; #pragma unroll
;                 for (int j = 0; j < 4; ++j) { u32x2 w; w.x = pk2(v[j][0], v[j][1]); w.y = pk2(v[j][2], v[j][3]); xr[64 * j] = w; }
;                 if (lane == 0) rinv[row] = 1.0f / sqrtf(s * (1.0f / DM) + EPS);
;             } }
.LBB0_733:
.LBB0_734:
	v_mul_f32_e32 v66, v17, v17
	v_mul_f32_e32 v67, v19, v19
	v_fmac_f32_e32 v66, v16, v16
	v_fmac_f32_e32 v67, v18, v18
	v_add_f32_e32 v66, v66, v67
	v_mul_f32_e32 v67, v21, v21
	v_mul_f32_e32 v68, v23, v23
	v_fmac_f32_e32 v67, v20, v20
	v_fmac_f32_e32 v68, v22, v22
	v_add_f32_e32 v67, v67, v68
	v_add_f32_e32 v66, v66, v67
	v_mul_f32_e32 v67, v25, v25
	v_mul_f32_e32 v68, v27, v27
	v_fmac_f32_e32 v67, v24, v24
	v_fmac_f32_e32 v68, v26, v26
	v_add_f32_e32 v67, v67, v68
	v_add_f32_e32 v66, v67, v66
	v_mul_f32_e32 v67, v29, v29
	v_mul_f32_e32 v68, v31, v31
	v_fmac_f32_e32 v67, v28, v28
	v_fmac_f32_e32 v68, v30, v30
	v_add_f32_e32 v67, v67, v68
	v_add_f32_e32 v66, v67, v66
	s_nop 0
	v_bfe_u32 v68, v16, 16, 1
	v_add3_u32 v16, v16, v68, s37
	v_lshrrev_b32_e32 v68, 16, v16
	s_waitcnt lgkmcnt(0)
	s_nop 1
	v_add_f32_dpp v66, v66, v66 quad_perm:[1,0,3,2] row_mask:0xf bank_mask:0xf
	s_nop 0
	s_waitcnt lgkmcnt(0)
	s_nop 1
	v_add_f32_dpp v66, v66, v66 quad_perm:[2,3,0,1] row_mask:0xf bank_mask:0xf
	s_nop 0
	s_waitcnt lgkmcnt(0)
	s_nop 1
	v_add_f32_dpp v66, v66, v66 row_half_mirror row_mask:0xf bank_mask:0xf
	s_nop 0
	s_waitcnt lgkmcnt(0)
	s_nop 1
	v_add_f32_dpp v66, v66, v66 row_mirror row_mask:0xf bank_mask:0xf
	ds_bpermute_b32 v67, v105, v66
	s_waitcnt lgkmcnt(0)
	v_add_f32_e32 v16, v66, v67
	v_bfe_u32 v67, v17, 16, 1
	v_add3_u32 v17, v17, v67, s37
	v_and_or_b32 v68, v17, s57, v68
	v_bfe_u32 v17, v18, 16, 1
	v_add3_u32 v17, v18, v17, s37
	v_bfe_u32 v18, v19, 16, 1
	v_lshrrev_b32_e32 v17, 16, v17
	v_add3_u32 v18, v19, v18, s37
	v_and_or_b32 v69, v18, s57, v17
	v_bfe_u32 v17, v20, 16, 1
	v_add3_u32 v17, v20, v17, s37
	v_bfe_u32 v18, v21, 16, 1
	v_lshrrev_b32_e32 v17, 16, v17
	v_add3_u32 v18, v21, v18, s37
	v_and_or_b32 v18, v18, s57, v17
	v_bfe_u32 v17, v22, 16, 1
	v_add3_u32 v17, v22, v17, s37
	v_bfe_u32 v19, v23, 16, 1
	v_lshrrev_b32_e32 v17, 16, v17
	v_add3_u32 v19, v23, v19, s37
	v_and_or_b32 v19, v19, s57, v17
	v_bfe_u32 v17, v24, 16, 1
	flat_store_dwordx2 v[64:65], v[18:19] offset:512
	v_add3_u32 v17, v24, v17, s37
	v_bfe_u32 v18, v25, 16, 1
	v_lshrrev_b32_e32 v17, 16, v17
	v_add3_u32 v18, v25, v18, s37
	v_and_or_b32 v18, v18, s57, v17
	v_bfe_u32 v17, v26, 16, 1
	v_add3_u32 v17, v26, v17, s37
	v_bfe_u32 v19, v27, 16, 1
	v_lshrrev_b32_e32 v17, 16, v17
	v_add3_u32 v19, v27, v19, s37
	v_and_or_b32 v19, v19, s57, v17
	v_bfe_u32 v17, v28, 16, 1
	flat_store_dwordx2 v[64:65], v[18:19] offset:1024
	v_add3_u32 v17, v28, v17, s37
	v_bfe_u32 v18, v29, 16, 1
	ds_bpermute_b32 v66, v106, v16
	v_lshrrev_b32_e32 v17, 16, v17
	v_add3_u32 v18, v29, v18, s37
	v_and_or_b32 v18, v18, s57, v17
	v_bfe_u32 v17, v30, 16, 1
	v_add3_u32 v17, v30, v17, s37
	v_bfe_u32 v19, v31, 16, 1
	v_lshrrev_b32_e32 v17, 16, v17
	v_add3_u32 v19, v31, v19, s37
	v_and_or_b32 v19, v19, s57, v17
	flat_store_dwordx2 v[64:65], v[68:69]
	flat_store_dwordx2 v[64:65], v[18:19] offset:1536
	s_and_saveexec_b64 s[86:87], s[38:39]
	s_cbranch_execz .LBB0_736
	s_waitcnt lgkmcnt(0)
	v_add_f32_e32 v16, v16, v66
	v_fmamk_f32 v16, v16, 0x3a800000, v217
	v_mul_f32_e32 v17, 0x4f800000, v16
	v_cmp_gt_f32_e32 vcc, s59, v16
	s_nop 1
	v_cndmask_b32_e32 v16, v16, v17, vcc
	v_sqrt_f32_e32 v17, v16
	s_nop 0
	v_add_u32_e32 v18, -1, v17
	v_fma_f32 v20, -v18, v17, v16
	v_add_u32_e32 v19, 1, v17
	v_cmp_ge_f32_e64 s[42:43], 0, v20
	s_nop 1
	v_cndmask_b32_e64 v18, v17, v18, s[42:43]
	v_fma_f32 v17, -v19, v17, v16
	v_cmp_lt_f32_e64 s[42:43], 0, v17
	s_nop 1
	v_cndmask_b32_e64 v17, v18, v19, s[42:43]
	v_mul_f32_e32 v18, 0x37800000, v17
	v_cndmask_b32_e32 v17, v17, v18, vcc
	v_cmp_class_f32_e32 vcc, v16, v218
	s_nop 1
	v_cndmask_b32_e32 v16, v17, v16, vcc
	v_div_scale_f32 v17, s[10:11], v16, v16, 1.0
	v_rcp_f32_e32 v18, v17
	s_lshl_b64 s[10:11], s[84:85], 2
	s_add_u32 s10, s5, s10
	s_addc_u32 s11, s6, s11
	v_fma_f32 v19, -v17, v18, 1.0
	v_fmac_f32_e32 v18, v19, v18
	v_div_scale_f32 v19, vcc, 1.0, v16, 1.0
	v_mul_f32_e32 v20, v19, v18
	v_fma_f32 v21, -v17, v20, v19
	v_fmac_f32_e32 v20, v21, v18
	v_fma_f32 v17, -v17, v20, v19
	v_div_fmas_f32 v17, v17, v18, v20
	v_div_fixup_f32 v18, v17, v16, 1.0
	v_mov_b64_e32 v[16:17], s[10:11]
	flat_store_dword v[16:17], v18

; __device__ __forceinline__ float shx(float v, int m, int lane) { return __builtin_bit_cast(float, __builtin_amdgcn_ds_bpermute((lane ^ m) << 2, __builtin_bit_cast(int, v))); }
; template <int RB> __device__ __forceinline__ void res_phase(float* xout, const bf16_t* mix, const float* ssp, const float* gain, bf16_t* XN, float* rinv, int gw, int ngw, int lane) {
;     ...
;     for (int row0 = rbase; row0 < rend; row0 += rstep) {
;         float ps[RB]; u32x2 xw[RB][4], mw[RB][4];
; #pragma unroll
;         for (int i = 0; i < RB; ++i) { const int row = row0 + i; ps[i] = ssp[(size_t)row * 16 + (lane & 15)];
;             const u32x2* xr = (const u32x2*)(XN + (size_t)row * DM) + lane; const u32x2* mr = (const u32x2*)(mix + (size_t)row * DM) + lane;
; #pragma unroll
;             for (int j = 0; j < 4; ++j) { xw[i][j] = xr[64 * j]; mw[i][j] = mr[64 * j]; } }
; #pragma unroll
;         for (int i = 0; i < RB; ++i) { const int row = row0 + i; float p = ps[i];
;             p += shx(p, 1, lane); p += shx(p, 2, lane); p += shx(p, 4, lane); p += shx(p, 8, lane);
;             const float rm = 1.0f / sqrtf(p * (1.0f / DM) + EPS);
;             f32x4 v[4]; float s = 0.f;
; #pragma unroll
;             for (int j = 0; j < 4; ++j) { const u32x2 a = xw[i][j], m = mw[i][j];
;                 f32x4 xv; xv[0] = __builtin_bit_cast(float, a.x << 16); xv[1] = __builtin_bit_cast(float, a.x & 0xffff0000u); xv[2] = __builtin_bit_cast(float, a.y << 16); xv[3] = __builtin_bit_cast(float, a.y & 0xffff0000u);
;                 f32x4 mv; mv[0] = __builtin_bit_cast(float, m.x << 16); mv[1] = __builtin_bit_cast(float, m.x & 0xffff0000u); mv[2] = __builtin_bit_cast(float, m.y << 16); mv[3] = __builtin_bit_cast(float, m.y & 0xffff0000u);
;                 v[j] = xv + mv * rm * gv[j]; s += (v[j][0] * v[j][0] + v[j][1] * v[j][1]) + (v[j][2] * v[j][2] + v[j][3] * v[j][3]); }
;             if (xout) { f32x4* xo = (f32x4*)(xout + (size_t)row * DM) + lane;
; #pragma unroll
;                 for (int j = 0; j < 4; ++j) xo[64 * j] = v[j];
.LBB0_737:
	s_nop 0
	v_lshlrev_b32_e32 v22, 16, v61
	v_and_b32_e32 v23, 0xffff0000, v61
	v_lshlrev_b32_e32 v24, 16, v56
	v_and_b32_e32 v25, 0xffff0000, v56
	s_waitcnt lgkmcnt(0)
	s_nop 1
	v_add_f32_dpp v16, v107, v107 quad_perm:[1,0,3,2] row_mask:0xf bank_mask:0xf
	s_nop 0
	v_lshlrev_b32_e32 v26, 16, v57
	v_and_b32_e32 v27, 0xffff0000, v57
	v_lshlrev_b32_e32 v30, 16, v52
	v_and_b32_e32 v31, 0xffff0000, v52
	s_waitcnt lgkmcnt(0)
	s_nop 1
	v_add_f32_dpp v16, v16, v16 quad_perm:[2,3,0,1] row_mask:0xf bank_mask:0xf
	s_nop 0
	v_lshlrev_b32_e32 v52, 16, v53
	v_and_b32_e32 v53, 0xffff0000, v53
	s_waitcnt lgkmcnt(0)
	s_nop 1
	v_add_f32_dpp v16, v16, v16 row_half_mirror row_mask:0xf bank_mask:0xf
	s_nop 0
	s_waitcnt lgkmcnt(0)
	s_nop 1
	v_add_f32_dpp v16, v16, v16 row_mirror row_mask:0xf bank_mask:0xf
	v_fmamk_f32 v16, v16, 0x3a800000, v217
	v_cmp_gt_f32_e32 vcc, s59, v16
	v_mul_f32_e32 v17, 0x4f800000, v16
	s_nop 0
	v_cndmask_b32_e32 v16, v16, v17, vcc
	v_sqrt_f32_e32 v17, v16
	s_nop 0
	v_add_u32_e32 v18, -1, v17
	v_fma_f32 v19, -v18, v17, v16
	v_cmp_ge_f32_e64 s[42:43], 0, v19
	v_add_u32_e32 v19, 1, v17
	s_nop 0
	v_cndmask_b32_e64 v18, v17, v18, s[42:43]
	v_fma_f32 v17, -v19, v17, v16
	v_cmp_lt_f32_e64 s[42:43], 0, v17
	s_nop 1
	v_cndmask_b32_e64 v17, v18, v19, s[42:43]
	v_mul_f32_e32 v18, 0x37800000, v17
	v_cndmask_b32_e32 v17, v17, v18, vcc
	v_cmp_class_f32_e32 vcc, v16, v218
	s_nop 1
	v_cndmask_b32_e32 v16, v17, v16, vcc
	v_div_scale_f32 v17, s[10:11], v16, v16, 1.0
	v_rcp_f32_e32 v18, v17
	s_nop 0
	v_fma_f32 v19, -v17, v18, 1.0
	v_fmac_f32_e32 v18, v19, v18
	v_div_scale_f32 v19, vcc, 1.0, v16, 1.0
	v_mul_f32_e32 v20, v19, v18
	v_fma_f32 v21, -v17, v20, v19
	v_fmac_f32_e32 v20, v21, v18
	v_fma_f32 v17, -v17, v20, v19
	v_div_fmas_f32 v17, v17, v18, v20
	v_div_fixup_f32 v28, v17, v16, 1.0
	v_lshlrev_b32_e32 v20, 16, v60
	v_and_b32_e32 v21, 0xffff0000, v60
	v_lshlrev_b32_e32 v16, 16, v62
	v_and_b32_e32 v17, 0xffff0000, v62
	v_lshlrev_b32_e32 v18, 16, v63
	v_and_b32_e32 v19, 0xffff0000, v63
	v_pk_mul_f32 v[20:21], v[28:29], v[20:21] op_sel_hi:[0,1]
	v_pk_mul_f32 v[22:23], v[28:29], v[22:23] op_sel_hi:[0,1]
	v_pk_fma_f32 v[18:19], v[2:3], v[22:23], v[18:19]
	v_pk_fma_f32 v[16:17], v[0:1], v[20:21], v[16:17]
	v_lshlrev_b32_e32 v20, 16, v58
	v_and_b32_e32 v21, 0xffff0000, v58
	v_lshlrev_b32_e32 v22, 16, v59
	v_and_b32_e32 v23, 0xffff0000, v59
	v_pk_mul_f32 v[24:25], v[28:29], v[24:25] op_sel_hi:[0,1]
	v_pk_mul_f32 v[26:27], v[28:29], v[26:27] op_sel_hi:[0,1]
	v_pk_fma_f32 v[22:23], v[6:7], v[26:27], v[22:23]
	v_pk_fma_f32 v[20:21], v[4:5], v[24:25], v[20:21]
	v_lshlrev_b32_e32 v24, 16, v54
	v_and_b32_e32 v25, 0xffff0000, v54
	v_lshlrev_b32_e32 v26, 16, v55
	v_and_b32_e32 v27, 0xffff0000, v55
	v_pk_mul_f32 v[30:31], v[28:29], v[30:31] op_sel_hi:[0,1]
	v_pk_mul_f32 v[52:53], v[28:29], v[52:53] op_sel_hi:[0,1]
	v_pk_fma_f32 v[26:27], v[10:11], v[52:53], v[26:27]
	v_pk_fma_f32 v[24:25], v[8:9], v[30:31], v[24:25]
	v_lshlrev_b32_e32 v52, 16, v48
	v_and_b32_e32 v53, 0xffff0000, v48
	v_lshlrev_b32_e32 v30, 16, v49
	v_and_b32_e32 v31, 0xffff0000, v49
	v_lshlrev_b32_e32 v48, 16, v50
	v_and_b32_e32 v49, 0xffff0000, v50
	v_lshlrev_b32_e32 v50, 16, v51
	v_and_b32_e32 v51, 0xffff0000, v51
	v_pk_mul_f32 v[48:49], v[28:29], v[48:49] op_sel_hi:[0,1]
	v_pk_mul_f32 v[28:29], v[28:29], v[50:51] op_sel_hi:[0,1]
	v_pk_fma_f32 v[30:31], v[14:15], v[28:29], v[30:31]
	v_pk_fma_f32 v[28:29], v[12:13], v[48:49], v[52:53]
	s_and_b64 vcc, exec, s[40:41]
	s_cbranch_vccnz .LBB0_739
	s_lshl_b64 s[10:11], s[82:83], 12
	v_lshl_add_u64 v[48:49], v[38:39], 0, s[10:11]
	global_store_dwordx4 v[48:49], v[16:19], off
	global_store_dwordx4 v[48:49], v[20:23], off offset:1024
	global_store_dwordx4 v[48:49], v[24:27], off offset:2048
	global_store_dwordx4 v[48:49], v[28:31], off offset:3072
	s_cbranch_execnz .LBB0_718
	s_branch .LBB0_740
; __device__ __forceinline__ unsigned pk2(float lo, float hi) { return f2bf(lo) | (f2bf(hi) << 16); }
; template <int RB> __device__ __forceinline__ void res_phase(float* xout, const bf16_t* mix, const float* ssp, const float* gain, bf16_t* XN, float* rinv, int gw, int ngw, int lane) {
;     ...
;             } else {
;                 s = wave_sum(s, lane); u32x2* xr = (u32x2*)(XN + (size_t)row * DM) + lane;
; #pragma unroll
;                 for (int j = 0; j < 4; ++j) { u32x2 w; w.x = pk2(v[j][0], v[j][1]); w.y = pk2(v[j][2], v[j][3]); xr[64 * j] = w; }
;                 if (lane == 0) rinv[row] = 1.0f / sqrtf(s * (1.0f / DM) + EPS);
;             } }
;     }
.LBB0_739:
.LBB0_740:
	v_mul_f32_e32 v48, v17, v17
	v_mul_f32_e32 v49, v19, v19
	v_fmac_f32_e32 v48, v16, v16
	v_fmac_f32_e32 v49, v18, v18
	v_add_f32_e32 v48, v48, v49
	v_mul_f32_e32 v49, v21, v21
	v_mul_f32_e32 v50, v23, v23
	v_fmac_f32_e32 v49, v20, v20
	v_fmac_f32_e32 v50, v22, v22
	v_add_f32_e32 v49, v49, v50
	v_add_f32_e32 v48, v48, v49
	v_mul_f32_e32 v49, v25, v25
	v_mul_f32_e32 v50, v27, v27
	v_fmac_f32_e32 v49, v24, v24
	v_fmac_f32_e32 v50, v26, v26
	v_add_f32_e32 v49, v49, v50
	v_add_f32_e32 v48, v49, v48
	v_mul_f32_e32 v49, v29, v29
	v_mul_f32_e32 v50, v31, v31
	v_fmac_f32_e32 v49, v28, v28
	v_fmac_f32_e32 v50, v30, v30
	v_add_f32_e32 v49, v49, v50
	v_add_f32_e32 v48, v49, v48
	s_nop 0
	v_and_b32_sdwa v50, v18, v216 dst_sel:DWORD dst_unused:UNUSED_PAD src0_sel:WORD_1 src1_sel:DWORD
	v_and_b32_sdwa v51, v16, v216 dst_sel:DWORD dst_unused:UNUSED_PAD src0_sel:WORD_1 src1_sel:DWORD
	v_add3_u32 v51, v16, v51, s37
	v_add3_u32 v18, v18, v50, s37
	s_waitcnt lgkmcnt(0)
	s_nop 1
	v_add_f32_dpp v48, v48, v48 quad_perm:[1,0,3,2] row_mask:0xf bank_mask:0xf
	s_nop 0
	v_and_b32_sdwa v50, v17, v216 dst_sel:DWORD dst_unused:UNUSED_PAD src0_sel:WORD_1 src1_sel:DWORD
	v_add3_u32 v17, v17, v50, s37
	v_and_b32_e32 v17, 0xffff0000, v17
	s_waitcnt lgkmcnt(0)
	s_nop 1
	v_add_f32_dpp v48, v48, v48 quad_perm:[2,3,0,1] row_mask:0xf bank_mask:0xf
	s_nop 0
	s_waitcnt lgkmcnt(0)
	s_nop 1
	v_add_f32_dpp v48, v48, v48 row_half_mirror row_mask:0xf bank_mask:0xf
	s_nop 0
	s_waitcnt lgkmcnt(0)
	s_nop 1
	v_add_f32_dpp v48, v48, v48 row_mirror row_mask:0xf bank_mask:0xf
	ds_bpermute_b32 v49, v105, v48
	s_waitcnt lgkmcnt(0)
	v_add_f32_e32 v16, v48, v49
	v_and_b32_sdwa v49, v19, v216 dst_sel:DWORD dst_unused:UNUSED_PAD src0_sel:WORD_1 src1_sel:DWORD
	v_add3_u32 v19, v19, v49, s37
	v_and_b32_e32 v19, 0xffff0000, v19
	v_or_b32_sdwa v19, v19, v18 dst_sel:DWORD dst_unused:UNUSED_PAD src0_sel:DWORD src1_sel:WORD_1
	v_or_b32_sdwa v18, v17, v51 dst_sel:DWORD dst_unused:UNUSED_PAD src0_sel:DWORD src1_sel:WORD_1
	flat_store_dwordx2 v[46:47], v[18:19]
	v_and_b32_sdwa v18, v20, v216 dst_sel:DWORD dst_unused:UNUSED_PAD src0_sel:WORD_1 src1_sel:DWORD
	v_add3_u32 v18, v20, v18, s37
	v_and_b32_sdwa v19, v23, v216 dst_sel:DWORD dst_unused:UNUSED_PAD src0_sel:WORD_1 src1_sel:DWORD
	v_and_b32_sdwa v20, v21, v216 dst_sel:DWORD dst_unused:UNUSED_PAD src0_sel:WORD_1 src1_sel:DWORD
	v_and_b32_sdwa v17, v22, v216 dst_sel:DWORD dst_unused:UNUSED_PAD src0_sel:WORD_1 src1_sel:DWORD
	v_add3_u32 v19, v23, v19, s37
	v_add3_u32 v20, v21, v20, s37
	v_add3_u32 v17, v22, v17, s37
	v_and_b32_e32 v19, 0xffff0000, v19
	v_and_b32_e32 v20, 0xffff0000, v20
	v_or_b32_sdwa v19, v19, v17 dst_sel:DWORD dst_unused:UNUSED_PAD src0_sel:DWORD src1_sel:WORD_1
	v_or_b32_sdwa v18, v20, v18 dst_sel:DWORD dst_unused:UNUSED_PAD src0_sel:DWORD src1_sel:WORD_1
	flat_store_dwordx2 v[46:47], v[18:19] offset:512
	v_and_b32_sdwa v19, v27, v216 dst_sel:DWORD dst_unused:UNUSED_PAD src0_sel:WORD_1 src1_sel:DWORD
	v_and_b32_sdwa v20, v25, v216 dst_sel:DWORD dst_unused:UNUSED_PAD src0_sel:WORD_1 src1_sel:DWORD
	v_and_b32_sdwa v17, v26, v216 dst_sel:DWORD dst_unused:UNUSED_PAD src0_sel:WORD_1 src1_sel:DWORD
	v_and_b32_sdwa v18, v24, v216 dst_sel:DWORD dst_unused:UNUSED_PAD src0_sel:WORD_1 src1_sel:DWORD
	v_add3_u32 v19, v27, v19, s37
	v_add3_u32 v20, v25, v20, s37
	v_add3_u32 v18, v24, v18, s37
	v_add3_u32 v17, v26, v17, s37
	v_and_b32_e32 v19, 0xffff0000, v19
	v_and_b32_e32 v20, 0xffff0000, v20
	ds_bpermute_b32 v48, v106, v16
	v_or_b32_sdwa v19, v19, v17 dst_sel:DWORD dst_unused:UNUSED_PAD src0_sel:DWORD src1_sel:WORD_1
	v_or_b32_sdwa v18, v20, v18 dst_sel:DWORD dst_unused:UNUSED_PAD src0_sel:DWORD src1_sel:WORD_1
	flat_store_dwordx2 v[46:47], v[18:19] offset:1024
	v_and_b32_sdwa v19, v31, v216 dst_sel:DWORD dst_unused:UNUSED_PAD src0_sel:WORD_1 src1_sel:DWORD
	v_and_b32_sdwa v20, v29, v216 dst_sel:DWORD dst_unused:UNUSED_PAD src0_sel:WORD_1 src1_sel:DWORD
	v_and_b32_sdwa v17, v30, v216 dst_sel:DWORD dst_unused:UNUSED_PAD src0_sel:WORD_1 src1_sel:DWORD
	v_and_b32_sdwa v18, v28, v216 dst_sel:DWORD dst_unused:UNUSED_PAD src0_sel:WORD_1 src1_sel:DWORD
	v_add3_u32 v19, v31, v19, s37
	v_add3_u32 v20, v29, v20, s37
	v_add3_u32 v18, v28, v18, s37
	v_add3_u32 v17, v30, v17, s37
	v_and_b32_e32 v19, 0xffff0000, v19
	v_and_b32_e32 v20, 0xffff0000, v20
	v_or_b32_sdwa v19, v19, v17 dst_sel:DWORD dst_unused:UNUSED_PAD src0_sel:DWORD src1_sel:WORD_1
	v_or_b32_sdwa v18, v20, v18 dst_sel:DWORD dst_unused:UNUSED_PAD src0_sel:DWORD src1_sel:WORD_1
	flat_store_dwordx2 v[46:47], v[18:19] offset:1536
	s_and_saveexec_b64 s[42:43], s[38:39]
	s_cbranch_execz .LBB0_717
	s_waitcnt lgkmcnt(0)
	v_add_f32_e32 v16, v16, v48
	v_fmamk_f32 v16, v16, 0x3a800000, v217
	v_mul_f32_e32 v17, 0x4f800000, v16
	v_cmp_gt_f32_e32 vcc, s59, v16
	s_nop 1
	v_cndmask_b32_e32 v16, v16, v17, vcc
	v_sqrt_f32_e32 v17, v16
	s_nop 0
	v_add_u32_e32 v18, -1, v17
	v_fma_f32 v20, -v18, v17, v16
	v_add_u32_e32 v19, 1, v17
	v_cmp_ge_f32_e64 s[40:41], 0, v20
	s_nop 1
	v_cndmask_b32_e64 v18, v17, v18, s[40:41]
	v_fma_f32 v17, -v19, v17, v16
	v_cmp_lt_f32_e64 s[40:41], 0, v17
	s_nop 1
	v_cndmask_b32_e64 v17, v18, v19, s[40:41]
	v_mul_f32_e32 v18, 0x37800000, v17
	v_cndmask_b32_e32 v17, v17, v18, vcc
	v_cmp_class_f32_e32 vcc, v16, v218
	s_nop 1
	v_cndmask_b32_e32 v16, v17, v16, vcc
	v_div_scale_f32 v17, s[10:11], v16, v16, 1.0
	v_rcp_f32_e32 v18, v17
	s_lshl_b64 s[10:11], s[82:83], 2
	s_add_u32 s10, s5, s10
	s_addc_u32 s11, s6, s11
	v_fma_f32 v19, -v17, v18, 1.0
	v_fmac_f32_e32 v18, v19, v18
	v_div_scale_f32 v19, vcc, 1.0, v16, 1.0
	v_mul_f32_e32 v20, v19, v18
	v_fma_f32 v21, -v17, v20, v19
	v_fmac_f32_e32 v20, v21, v18
	v_fma_f32 v17, -v17, v20, v19
	v_div_fmas_f32 v17, v17, v18, v20
	v_div_fixup_f32 v18, v17, v16, 1.0
	v_mov_b64_e32 v[16:17], s[10:11]
	flat_store_dword v[16:17], v18
	s_branch .LBB0_717
